# loop-edge hoist: K-loop counter/pointer updates and exit compare moved from behind the closing barrier into the last MFMA group's shadow (8 GEMM loops)
# speedup vs baseline: 1.0048x; 1.0048x over previous
.LBB0_167:
	ds_read_b128 v[144:147], v151
	ds_read_b128 v[156:159], v151 offset:1024
	ds_read_b128 v[160:163], v151 offset:2048
	ds_read_b128 v[164:167], v151 offset:3072
	ds_read_b128 v[168:171], v152
	ds_read_b128 v[172:175], v152 offset:1024
	ds_read_b128 v[176:179], v152 offset:2048
	ds_read_b128 v[180:183], v152 offset:3072
	s_add_u32 s34, s30, 0xfff80080
	s_addc_u32 s35, s31, -1
	s_cmp_eq_u32 s72, 28
	s_cselect_b32 s37, s25, s35
	s_cselect_b32 s36, s62, s34
	s_cselect_b32 s35, s23, s71
	s_cselect_b32 s34, s63, s70
	v_lshl_add_u64 v[216:217], s[30:31], 0, v[136:137]
	s_add_i32 m0, s39, 0xc000
	ds_read_b128 v[184:187], v153
	ds_read_b128 v[188:191], v153 offset:1024
	ds_read_b128 v[192:195], v153 offset:2048
	ds_read_b128 v[196:199], v153 offset:3072
	ds_read_b128 v[200:203], v153 offset:4096
	ds_read_b128 v[204:207], v153 offset:5120
	ds_read_b128 v[208:211], v153 offset:6144
	ds_read_b128 v[212:215], v153 offset:7168
	global_load_lds_dwordx4 v[216:217], off
	v_lshl_add_u64 v[216:217], s[30:31], 0, v[138:139]
	s_add_i32 m0, s39, 0xe000
	s_nop 0
	global_load_lds_dwordx4 v[216:217], off
	s_waitcnt vmcnt(8)
	s_waitcnt lgkmcnt(0)
	s_barrier
	s_setprio 1
	s_waitcnt lgkmcnt(0)
	v_mfma_f32_16x16x32_bf16 v[124:127], v[144:147], v[184:187], v[124:127]
	v_mfma_f32_16x16x32_bf16 v[120:123], v[160:163], v[184:187], v[120:123]
	v_mfma_f32_16x16x32_bf16 v[116:119], v[144:147], v[192:195], v[116:119]
	v_mfma_f32_16x16x32_bf16 v[100:103], v[160:163], v[192:195], v[100:103]
	v_mfma_f32_16x16x32_bf16 v[92:95], v[144:147], v[200:203], v[92:95]
	v_mfma_f32_16x16x32_bf16 v[84:87], v[160:163], v[200:203], v[84:87]
	v_mfma_f32_16x16x32_bf16 v[76:79], v[144:147], v[208:211], v[76:79]
	v_mfma_f32_16x16x32_bf16 v[68:71], v[160:163], v[208:211], v[68:71]
	v_mfma_f32_16x16x32_bf16 v[124:127], v[156:159], v[188:191], v[124:127]
	v_mfma_f32_16x16x32_bf16 v[120:123], v[164:167], v[188:191], v[120:123]
	v_mfma_f32_16x16x32_bf16 v[116:119], v[156:159], v[196:199], v[116:119]
	v_mfma_f32_16x16x32_bf16 v[100:103], v[164:167], v[196:199], v[100:103]
	v_mfma_f32_16x16x32_bf16 v[92:95], v[156:159], v[204:207], v[92:95]
	v_mfma_f32_16x16x32_bf16 v[84:87], v[164:167], v[204:207], v[84:87]
	v_mfma_f32_16x16x32_bf16 v[76:79], v[156:159], v[212:215], v[76:79]
	v_mfma_f32_16x16x32_bf16 v[68:71], v[164:167], v[212:215], v[68:71]
	s_setprio 0
	s_setprio 1
	v_mfma_f32_16x16x32_bf16 v[112:115], v[168:171], v[184:187], v[112:115]
	v_mfma_f32_16x16x32_bf16 v[108:111], v[176:179], v[184:187], v[108:111]
	v_mfma_f32_16x16x32_bf16 v[104:107], v[168:171], v[192:195], v[104:107]
	v_mfma_f32_16x16x32_bf16 v[96:99], v[176:179], v[192:195], v[96:99]
	v_mfma_f32_16x16x32_bf16 v[88:91], v[168:171], v[200:203], v[88:91]
	v_mfma_f32_16x16x32_bf16 v[80:83], v[176:179], v[200:203], v[80:83]
	v_mfma_f32_16x16x32_bf16 v[72:75], v[168:171], v[208:211], v[72:75]
	v_mfma_f32_16x16x32_bf16 v[64:67], v[176:179], v[208:211], v[64:67]
	v_mfma_f32_16x16x32_bf16 v[112:115], v[172:175], v[188:191], v[112:115]
	v_mfma_f32_16x16x32_bf16 v[108:111], v[180:183], v[188:191], v[108:111]
	v_mfma_f32_16x16x32_bf16 v[104:107], v[172:175], v[196:199], v[104:107]
	v_mfma_f32_16x16x32_bf16 v[96:99], v[180:183], v[196:199], v[96:99]
	v_mfma_f32_16x16x32_bf16 v[88:91], v[172:175], v[204:207], v[88:91]
	v_mfma_f32_16x16x32_bf16 v[80:83], v[180:183], v[204:207], v[80:83]
	v_mfma_f32_16x16x32_bf16 v[72:75], v[172:175], v[212:215], v[72:75]
	v_mfma_f32_16x16x32_bf16 v[64:67], v[180:183], v[212:215], v[64:67]
	s_setprio 0
	s_barrier
	s_add_i32 s73, s60, s3
	v_lshl_add_u64 v[216:217], s[34:35], 0, v[132:133]
	s_mov_b32 m0, s73
	ds_read_b128 v[184:187], v153 offset:16384
	ds_read_b128 v[188:191], v153 offset:17408
	ds_read_b128 v[192:195], v153 offset:18432
	ds_read_b128 v[196:199], v153 offset:19456
	ds_read_b128 v[200:203], v153 offset:20480
	ds_read_b128 v[204:207], v153 offset:21504
	ds_read_b128 v[208:211], v153 offset:22528
	ds_read_b128 v[212:215], v153 offset:23552
	global_load_lds_dwordx4 v[216:217], off
	s_add_i32 m0, s73, 0x2000
	s_add_u32 s74, s34, 0x80000
	v_lshl_add_u64 v[218:219], s[34:35], 0, v[128:129]
	s_addc_u32 s75, s35, 0
	s_add_i32 s73, s61, s3
	global_load_lds_dwordx4 v[218:219], off
	v_lshl_add_u64 v[220:221], s[74:75], 0, v[132:133]
	s_mov_b32 m0, s73
	v_lshl_add_u64 v[222:223], s[36:37], 0, v[130:131]
	global_load_lds_dwordx4 v[220:221], off
	v_lshl_add_u64 v[220:221], s[74:75], 0, v[128:129]
	s_add_i32 m0, s73, 0x2000
	s_nop 0
	global_load_lds_dwordx4 v[220:221], off
	v_lshl_add_u64 v[220:221], s[36:37], 0, v[134:135]
	s_mov_b32 m0, s39
	s_nop 0
	global_load_lds_dwordx4 v[220:221], off
	s_mov_b32 m0, s40
	s_nop 0
	global_load_lds_dwordx4 v[222:223], off
	s_waitcnt vmcnt(8)
	s_waitcnt lgkmcnt(0)
	s_barrier
	s_setprio 1
	s_waitcnt lgkmcnt(0)
	v_mfma_f32_16x16x32_bf16 v[60:63], v[144:147], v[184:187], v[60:63]
	v_mfma_f32_16x16x32_bf16 v[52:55], v[160:163], v[184:187], v[52:55]
	v_mfma_f32_16x16x32_bf16 v[44:47], v[144:147], v[192:195], v[44:47]
	v_mfma_f32_16x16x32_bf16 v[36:39], v[160:163], v[192:195], v[36:39]
	v_mfma_f32_16x16x32_bf16 v[28:31], v[144:147], v[200:203], v[28:31]
	v_mfma_f32_16x16x32_bf16 v[20:23], v[160:163], v[200:203], v[20:23]
	v_mfma_f32_16x16x32_bf16 v[12:15], v[144:147], v[208:211], v[12:15]
	v_mfma_f32_16x16x32_bf16 v[4:7], v[160:163], v[208:211], v[4:7]
	v_mfma_f32_16x16x32_bf16 v[60:63], v[156:159], v[188:191], v[60:63]
	v_mfma_f32_16x16x32_bf16 v[52:55], v[164:167], v[188:191], v[52:55]
	v_mfma_f32_16x16x32_bf16 v[44:47], v[156:159], v[196:199], v[44:47]
	v_mfma_f32_16x16x32_bf16 v[36:39], v[164:167], v[196:199], v[36:39]
	v_mfma_f32_16x16x32_bf16 v[28:31], v[156:159], v[204:207], v[28:31]
	v_mfma_f32_16x16x32_bf16 v[20:23], v[164:167], v[204:207], v[20:23]
	v_mfma_f32_16x16x32_bf16 v[12:15], v[156:159], v[212:215], v[12:15]
	v_mfma_f32_16x16x32_bf16 v[4:7], v[164:167], v[212:215], v[4:7]
	s_setprio 0
	s_setprio 1
	v_mfma_f32_16x16x32_bf16 v[56:59], v[168:171], v[184:187], v[56:59]
	v_mfma_f32_16x16x32_bf16 v[48:51], v[176:179], v[184:187], v[48:51]
	v_mfma_f32_16x16x32_bf16 v[40:43], v[168:171], v[192:195], v[40:43]
	v_mfma_f32_16x16x32_bf16 v[32:35], v[176:179], v[192:195], v[32:35]
	v_mfma_f32_16x16x32_bf16 v[24:27], v[168:171], v[200:203], v[24:27]
	v_mfma_f32_16x16x32_bf16 v[16:19], v[176:179], v[200:203], v[16:19]
	v_mfma_f32_16x16x32_bf16 v[8:11], v[168:171], v[208:211], v[8:11]
	v_mfma_f32_16x16x32_bf16 v[0:3], v[176:179], v[208:211], v[0:3]
	v_mfma_f32_16x16x32_bf16 v[56:59], v[172:175], v[188:191], v[56:59]
	v_mfma_f32_16x16x32_bf16 v[48:51], v[180:183], v[188:191], v[48:51]
	v_mfma_f32_16x16x32_bf16 v[40:43], v[172:175], v[196:199], v[40:43]
	v_mfma_f32_16x16x32_bf16 v[32:35], v[180:183], v[196:199], v[32:35]
	v_mfma_f32_16x16x32_bf16 v[24:27], v[172:175], v[204:207], v[24:27]
	v_mfma_f32_16x16x32_bf16 v[16:19], v[180:183], v[204:207], v[16:19]
	v_mfma_f32_16x16x32_bf16 v[8:11], v[172:175], v[212:215], v[8:11]
	v_mfma_f32_16x16x32_bf16 v[0:3], v[180:183], v[212:215], v[0:3]
	s_setprio 0
	s_barrier
	s_add_i32 s73, 0, 0x18000
	v_add_u32_e32 v155, s73, v149
	s_add_i32 s74, 0, 0x1c000
	ds_read_b128 v[144:147], v155
	ds_read_b128 v[156:159], v155 offset:1024
	ds_read_b128 v[160:163], v155 offset:2048
	ds_read_b128 v[164:167], v155 offset:3072
	v_add_u32_e32 v155, s74, v149
	ds_read_b128 v[168:171], v155
	ds_read_b128 v[172:175], v155 offset:1024
	ds_read_b128 v[176:179], v155 offset:2048
	ds_read_b128 v[180:183], v155 offset:3072
	s_add_u32 s36, s36, 0x80000
	s_addc_u32 s37, s37, 0
	s_mov_b32 m0, s41
	v_lshl_add_u64 v[226:227], s[36:37], 0, v[134:135]
	ds_read_b128 v[184:187], v153 offset:32768
	ds_read_b128 v[188:191], v153 offset:33792
	ds_read_b128 v[192:195], v153 offset:34816
	ds_read_b128 v[196:199], v153 offset:35840
	ds_read_b128 v[200:203], v153 offset:36864
	ds_read_b128 v[204:207], v153 offset:37888
	ds_read_b128 v[208:211], v153 offset:38912
	ds_read_b128 v[212:215], v153 offset:39936
	global_load_lds_dwordx4 v[226:227], off
	v_lshl_add_u64 v[226:227], s[36:37], 0, v[130:131]
	s_mov_b32 m0, s42
	s_nop 0
	global_load_lds_dwordx4 v[226:227], off
	s_waitcnt vmcnt(8)
	s_waitcnt lgkmcnt(0)
	s_barrier
	s_setprio 1
	s_waitcnt lgkmcnt(0)
	v_mfma_f32_16x16x32_bf16 v[124:127], v[144:147], v[184:187], v[124:127]
	v_mfma_f32_16x16x32_bf16 v[120:123], v[160:163], v[184:187], v[120:123]
	v_mfma_f32_16x16x32_bf16 v[116:119], v[144:147], v[192:195], v[116:119]
	v_mfma_f32_16x16x32_bf16 v[100:103], v[160:163], v[192:195], v[100:103]
	v_mfma_f32_16x16x32_bf16 v[92:95], v[144:147], v[200:203], v[92:95]
	v_mfma_f32_16x16x32_bf16 v[84:87], v[160:163], v[200:203], v[84:87]
	v_mfma_f32_16x16x32_bf16 v[76:79], v[144:147], v[208:211], v[76:79]
	v_mfma_f32_16x16x32_bf16 v[68:71], v[160:163], v[208:211], v[68:71]
	v_mfma_f32_16x16x32_bf16 v[124:127], v[156:159], v[188:191], v[124:127]
	v_mfma_f32_16x16x32_bf16 v[120:123], v[164:167], v[188:191], v[120:123]
	v_mfma_f32_16x16x32_bf16 v[116:119], v[156:159], v[196:199], v[116:119]
	v_mfma_f32_16x16x32_bf16 v[100:103], v[164:167], v[196:199], v[100:103]
	v_mfma_f32_16x16x32_bf16 v[92:95], v[156:159], v[204:207], v[92:95]
	v_mfma_f32_16x16x32_bf16 v[84:87], v[164:167], v[204:207], v[84:87]
	v_mfma_f32_16x16x32_bf16 v[76:79], v[156:159], v[212:215], v[76:79]
	v_mfma_f32_16x16x32_bf16 v[68:71], v[164:167], v[212:215], v[68:71]
	s_setprio 0
	s_setprio 1
	v_mfma_f32_16x16x32_bf16 v[112:115], v[168:171], v[184:187], v[112:115]
	v_mfma_f32_16x16x32_bf16 v[108:111], v[176:179], v[184:187], v[108:111]
	v_mfma_f32_16x16x32_bf16 v[104:107], v[168:171], v[192:195], v[104:107]
	v_mfma_f32_16x16x32_bf16 v[96:99], v[176:179], v[192:195], v[96:99]
	v_mfma_f32_16x16x32_bf16 v[88:91], v[168:171], v[200:203], v[88:91]
	v_mfma_f32_16x16x32_bf16 v[80:83], v[176:179], v[200:203], v[80:83]
	v_mfma_f32_16x16x32_bf16 v[72:75], v[168:171], v[208:211], v[72:75]
	v_mfma_f32_16x16x32_bf16 v[64:67], v[176:179], v[208:211], v[64:67]
	v_mfma_f32_16x16x32_bf16 v[112:115], v[172:175], v[188:191], v[112:115]
	v_mfma_f32_16x16x32_bf16 v[108:111], v[180:183], v[188:191], v[108:111]
	v_mfma_f32_16x16x32_bf16 v[104:107], v[172:175], v[196:199], v[104:107]
	v_mfma_f32_16x16x32_bf16 v[96:99], v[180:183], v[196:199], v[96:99]
	v_mfma_f32_16x16x32_bf16 v[88:91], v[172:175], v[204:207], v[88:91]
	v_mfma_f32_16x16x32_bf16 v[80:83], v[180:183], v[204:207], v[80:83]
	v_mfma_f32_16x16x32_bf16 v[72:75], v[172:175], v[212:215], v[72:75]
	v_mfma_f32_16x16x32_bf16 v[64:67], v[180:183], v[212:215], v[64:67]
	s_setprio 0
	s_barrier
	s_add_i32 s36, s73, s3
	v_lshl_add_u64 v[216:217], v[216:217], 0, s[18:19]
	s_mov_b32 m0, s36
	ds_read_b128 v[184:187], v153 offset:49152
	ds_read_b128 v[188:191], v153 offset:50176
	ds_read_b128 v[192:195], v153 offset:51200
	ds_read_b128 v[196:199], v153 offset:52224
	ds_read_b128 v[200:203], v153 offset:53248
	ds_read_b128 v[204:207], v153 offset:54272
	ds_read_b128 v[208:211], v153 offset:55296
	ds_read_b128 v[212:215], v153 offset:56320
	global_load_lds_dwordx4 v[216:217], off
	s_add_i32 m0, s36, 0x2000
	s_add_u32 s34, s34, 0x80080
	v_lshl_add_u64 v[216:217], v[218:219], 0, s[18:19]
	s_addc_u32 s35, s35, 0
	s_add_i32 s36, s74, s3
	global_load_lds_dwordx4 v[216:217], off
	v_lshl_add_u64 v[216:217], s[34:35], 0, v[132:133]
	s_mov_b32 m0, s36
	s_nop 0
	global_load_lds_dwordx4 v[216:217], off
	v_lshl_add_u64 v[216:217], s[34:35], 0, v[128:129]
	s_add_i32 m0, s36, 0x2000
	s_nop 0
	global_load_lds_dwordx4 v[216:217], off
	v_lshl_add_u64 v[216:217], v[220:221], 0, s[18:19]
	s_mov_b32 m0, s44
	s_nop 0
	global_load_lds_dwordx4 v[216:217], off
	v_lshl_add_u64 v[216:217], v[222:223], 0, s[18:19]
	s_mov_b32 m0, s45
	s_nop 0
	global_load_lds_dwordx4 v[216:217], off
	s_waitcnt vmcnt(8)
	s_waitcnt lgkmcnt(0)
	s_barrier
	s_setprio 1
	s_waitcnt lgkmcnt(0)
	v_mfma_f32_16x16x32_bf16 v[60:63], v[144:147], v[184:187], v[60:63]
	v_mfma_f32_16x16x32_bf16 v[52:55], v[160:163], v[184:187], v[52:55]
	v_mfma_f32_16x16x32_bf16 v[44:47], v[144:147], v[192:195], v[44:47]
	v_mfma_f32_16x16x32_bf16 v[36:39], v[160:163], v[192:195], v[36:39]
	v_mfma_f32_16x16x32_bf16 v[28:31], v[144:147], v[200:203], v[28:31]
	v_mfma_f32_16x16x32_bf16 v[20:23], v[160:163], v[200:203], v[20:23]
	v_mfma_f32_16x16x32_bf16 v[12:15], v[144:147], v[208:211], v[12:15]
	v_mfma_f32_16x16x32_bf16 v[4:7], v[160:163], v[208:211], v[4:7]
	v_mfma_f32_16x16x32_bf16 v[60:63], v[156:159], v[188:191], v[60:63]
	v_mfma_f32_16x16x32_bf16 v[52:55], v[164:167], v[188:191], v[52:55]
	v_mfma_f32_16x16x32_bf16 v[44:47], v[156:159], v[196:199], v[44:47]
	v_mfma_f32_16x16x32_bf16 v[36:39], v[164:167], v[196:199], v[36:39]
	v_mfma_f32_16x16x32_bf16 v[28:31], v[156:159], v[204:207], v[28:31]
	v_mfma_f32_16x16x32_bf16 v[20:23], v[164:167], v[204:207], v[20:23]
	v_mfma_f32_16x16x32_bf16 v[12:15], v[156:159], v[212:215], v[12:15]
	v_mfma_f32_16x16x32_bf16 v[4:7], v[164:167], v[212:215], v[4:7]
	s_setprio 0
	s_setprio 1
	v_mfma_f32_16x16x32_bf16 v[56:59], v[168:171], v[184:187], v[56:59]
	s_add_i32 s72, s72, 2
	v_mfma_f32_16x16x32_bf16 v[48:51], v[176:179], v[184:187], v[48:51]
	s_add_u32 s30, s30, 0x100
	v_mfma_f32_16x16x32_bf16 v[40:43], v[168:171], v[192:195], v[40:43]
	s_addc_u32 s31, s31, 0
	v_mfma_f32_16x16x32_bf16 v[32:35], v[176:179], v[192:195], v[32:35]
	s_add_u32 s70, s70, 0x100
	v_mfma_f32_16x16x32_bf16 v[24:27], v[168:171], v[200:203], v[24:27]
	s_addc_u32 s71, s71, 0
	v_mfma_f32_16x16x32_bf16 v[16:19], v[176:179], v[200:203], v[16:19]
	s_cmp_gt_u32 s72, 29
	v_mfma_f32_16x16x32_bf16 v[8:11], v[168:171], v[208:211], v[8:11]
	v_mfma_f32_16x16x32_bf16 v[0:3], v[176:179], v[208:211], v[0:3]
	v_mfma_f32_16x16x32_bf16 v[56:59], v[172:175], v[188:191], v[56:59]
	v_mfma_f32_16x16x32_bf16 v[48:51], v[180:183], v[188:191], v[48:51]
	v_mfma_f32_16x16x32_bf16 v[40:43], v[172:175], v[196:199], v[40:43]
	v_mfma_f32_16x16x32_bf16 v[32:35], v[180:183], v[196:199], v[32:35]
	v_mfma_f32_16x16x32_bf16 v[24:27], v[172:175], v[204:207], v[24:27]
	v_mfma_f32_16x16x32_bf16 v[16:19], v[180:183], v[204:207], v[16:19]
	v_mfma_f32_16x16x32_bf16 v[8:11], v[172:175], v[212:215], v[8:11]
	v_mfma_f32_16x16x32_bf16 v[0:3], v[180:183], v[212:215], v[0:3]
	s_setprio 0
	s_barrier
	s_cbranch_scc0 .LBB0_167
	s_and_b64 vcc, exec, s[20:21]
	s_cbranch_vccz .LBB0_170
	s_barrier

.LBB0_362:
	s_add_u32 s28, s22, s30
	s_addc_u32 s29, s23, s31
	s_add_u32 s84, s28, 0x100
	s_addc_u32 s85, s29, 0
	s_and_b64 s[28:29], s[36:37], exec
	s_cselect_b32 s29, s85, s83
	s_cselect_b32 s28, s84, s96
	s_add_u32 s84, s80, s30
	s_addc_u32 s85, s81, s31
	s_and_b64 s[36:37], s[36:37], exec
	s_cselect_b32 s37, s85, s97
	s_cselect_b32 s36, s84, s62
	s_mov_b32 m0, s45
	v_lshl_add_u64 v[172:173], s[36:37], 0, v[182:183]
	v_lshl_add_u64 v[222:223], s[36:37], 0, v[180:181]
	s_add_u32 s36, s36, s34
	ds_read_b128 v[194:197], v190 offset:16384
	ds_read_b128 v[198:201], v190 offset:17408
	ds_read_b128 v[202:205], v190 offset:18432
	ds_read_b128 v[206:209], v190 offset:19456
	ds_read_b128 v[210:213], v190 offset:20480
	ds_read_b128 v[214:217], v190 offset:21504
	ds_read_b128 v[218:221], v190 offset:22528
	ds_read_b128 v[226:229], v190 offset:23552
	global_load_lds_dwordx4 v[172:173], off
	s_mov_b32 m0, s58
	s_addc_u32 s37, s37, s35
	global_load_lds_dwordx4 v[222:223], off
	v_lshl_add_u64 v[230:231], s[36:37], 0, v[182:183]
	s_mov_b32 m0, s59
	v_lshl_add_u64 v[232:233], s[36:37], 0, v[180:181]
	global_load_lds_dwordx4 v[230:231], off
	s_mov_b32 m0, s60
	v_lshl_add_u64 v[234:235], s[28:29], 0, v[178:179]
	global_load_lds_dwordx4 v[232:233], off
	s_mov_b32 m0, s44
	v_lshl_add_u64 v[236:237], s[28:29], 0, v[176:177]
	global_load_lds_dwordx4 v[234:235], off
	s_mov_b32 m0, s61
	s_nop 0
	global_load_lds_dwordx4 v[236:237], off
	s_waitcnt vmcnt(8)
	s_waitcnt lgkmcnt(0)
	s_barrier
	s_setprio 1
	s_waitcnt lgkmcnt(0)
	v_mfma_f32_16x16x32_bf16 v[60:63], v[144:147], v[194:197], v[60:63]
	v_mfma_f32_16x16x32_bf16 v[56:59], v[152:155], v[194:197], v[56:59]
	v_mfma_f32_16x16x32_bf16 v[44:47], v[144:147], v[202:205], v[44:47]
	v_mfma_f32_16x16x32_bf16 v[40:43], v[152:155], v[202:205], v[40:43]
	v_mfma_f32_16x16x32_bf16 v[28:31], v[144:147], v[210:213], v[28:31]
	v_mfma_f32_16x16x32_bf16 v[24:27], v[152:155], v[210:213], v[24:27]
	v_mfma_f32_16x16x32_bf16 v[12:15], v[144:147], v[218:221], v[12:15]
	v_mfma_f32_16x16x32_bf16 v[8:11], v[152:155], v[218:221], v[8:11]
	v_mfma_f32_16x16x32_bf16 v[60:63], v[148:151], v[198:201], v[60:63]
	v_mfma_f32_16x16x32_bf16 v[56:59], v[156:159], v[198:201], v[56:59]
	v_mfma_f32_16x16x32_bf16 v[44:47], v[148:151], v[206:209], v[44:47]
	v_mfma_f32_16x16x32_bf16 v[40:43], v[156:159], v[206:209], v[40:43]
	v_mfma_f32_16x16x32_bf16 v[28:31], v[148:151], v[214:217], v[28:31]
	v_mfma_f32_16x16x32_bf16 v[24:27], v[156:159], v[214:217], v[24:27]
	v_mfma_f32_16x16x32_bf16 v[12:15], v[148:151], v[226:229], v[12:15]
	v_mfma_f32_16x16x32_bf16 v[8:11], v[156:159], v[226:229], v[8:11]
	s_setprio 0
	s_setprio 1
	v_mfma_f32_16x16x32_bf16 v[52:55], v[128:131], v[194:197], v[52:55]
	v_mfma_f32_16x16x32_bf16 v[48:51], v[136:139], v[194:197], v[48:51]
	v_mfma_f32_16x16x32_bf16 v[36:39], v[128:131], v[202:205], v[36:39]
	v_mfma_f32_16x16x32_bf16 v[32:35], v[136:139], v[202:205], v[32:35]
	v_mfma_f32_16x16x32_bf16 v[20:23], v[128:131], v[210:213], v[20:23]
	v_mfma_f32_16x16x32_bf16 v[16:19], v[136:139], v[210:213], v[16:19]
	v_mfma_f32_16x16x32_bf16 v[4:7], v[128:131], v[218:221], v[4:7]
	v_mfma_f32_16x16x32_bf16 v[0:3], v[136:139], v[218:221], v[0:3]
	v_mfma_f32_16x16x32_bf16 v[52:55], v[132:135], v[198:201], v[52:55]
	v_mfma_f32_16x16x32_bf16 v[48:51], v[140:143], v[198:201], v[48:51]
	v_mfma_f32_16x16x32_bf16 v[36:39], v[132:135], v[206:209], v[36:39]
	v_mfma_f32_16x16x32_bf16 v[32:35], v[140:143], v[206:209], v[32:35]
	v_mfma_f32_16x16x32_bf16 v[20:23], v[132:135], v[214:217], v[20:23]
	v_mfma_f32_16x16x32_bf16 v[16:19], v[140:143], v[214:217], v[16:19]
	v_mfma_f32_16x16x32_bf16 v[4:7], v[132:135], v[226:229], v[4:7]
	v_mfma_f32_16x16x32_bf16 v[0:3], v[140:143], v[226:229], v[0:3]
	s_setprio 0
	s_barrier
	s_add_i32 s36, 0, 0x18000
	s_add_i32 s37, 0, 0x1c000
	v_add_u32_e32 v140, s36, v189
	v_add_u32_e32 v156, s37, v189
	ds_read_b128 v[128:131], v140
	ds_read_b128 v[132:135], v140 offset:1024
	ds_read_b128 v[136:139], v140 offset:2048
	ds_read_b128 v[140:143], v140 offset:3072
	ds_read_b128 v[144:147], v156
	ds_read_b128 v[148:151], v156 offset:1024
	ds_read_b128 v[152:155], v156 offset:2048
	ds_read_b128 v[156:159], v156 offset:3072
	s_add_u32 s28, s28, s34
	s_addc_u32 s29, s29, s35
	s_mov_b32 m0, s69
	v_lshl_add_u64 v[178:179], s[28:29], 0, v[178:179]
	ds_read_b128 v[180:183], v190 offset:32768
	ds_read_b128 v[194:197], v190 offset:33792
	ds_read_b128 v[198:201], v190 offset:34816
	ds_read_b128 v[202:205], v190 offset:35840
	ds_read_b128 v[206:209], v190 offset:36864
	ds_read_b128 v[210:213], v190 offset:37888
	ds_read_b128 v[214:217], v190 offset:38912
	ds_read_b128 v[218:221], v190 offset:39936
	global_load_lds_dwordx4 v[178:179], off
	v_lshl_add_u64 v[176:177], s[28:29], 0, v[176:177]
	s_mov_b32 m0, s72
	s_nop 0
	global_load_lds_dwordx4 v[176:177], off
	s_waitcnt vmcnt(8)
	s_waitcnt lgkmcnt(0)
	s_barrier
	s_setprio 1
	s_waitcnt lgkmcnt(0)
	v_mfma_f32_16x16x32_bf16 v[124:127], v[128:131], v[180:183], v[124:127]
	v_mfma_f32_16x16x32_bf16 v[120:123], v[136:139], v[180:183], v[120:123]
	v_mfma_f32_16x16x32_bf16 v[108:111], v[128:131], v[198:201], v[108:111]
	v_mfma_f32_16x16x32_bf16 v[104:107], v[136:139], v[198:201], v[104:107]
	v_mfma_f32_16x16x32_bf16 v[92:95], v[128:131], v[206:209], v[92:95]
	v_mfma_f32_16x16x32_bf16 v[88:91], v[136:139], v[206:209], v[88:91]
	v_mfma_f32_16x16x32_bf16 v[76:79], v[128:131], v[214:217], v[76:79]
	v_mfma_f32_16x16x32_bf16 v[72:75], v[136:139], v[214:217], v[72:75]
	v_mfma_f32_16x16x32_bf16 v[124:127], v[132:135], v[194:197], v[124:127]
	v_mfma_f32_16x16x32_bf16 v[120:123], v[140:143], v[194:197], v[120:123]
	v_mfma_f32_16x16x32_bf16 v[108:111], v[132:135], v[202:205], v[108:111]
	v_mfma_f32_16x16x32_bf16 v[104:107], v[140:143], v[202:205], v[104:107]
	v_mfma_f32_16x16x32_bf16 v[92:95], v[132:135], v[210:213], v[92:95]
	v_mfma_f32_16x16x32_bf16 v[88:91], v[140:143], v[210:213], v[88:91]
	v_mfma_f32_16x16x32_bf16 v[76:79], v[132:135], v[218:221], v[76:79]
	v_mfma_f32_16x16x32_bf16 v[72:75], v[140:143], v[218:221], v[72:75]
	s_setprio 0
	s_setprio 1
	v_mfma_f32_16x16x32_bf16 v[116:119], v[144:147], v[180:183], v[116:119]
	v_mfma_f32_16x16x32_bf16 v[112:115], v[152:155], v[180:183], v[112:115]
	v_mfma_f32_16x16x32_bf16 v[100:103], v[144:147], v[198:201], v[100:103]
	v_mfma_f32_16x16x32_bf16 v[96:99], v[152:155], v[198:201], v[96:99]
	v_mfma_f32_16x16x32_bf16 v[84:87], v[144:147], v[206:209], v[84:87]
	v_mfma_f32_16x16x32_bf16 v[80:83], v[152:155], v[206:209], v[80:83]
	v_mfma_f32_16x16x32_bf16 v[68:71], v[144:147], v[214:217], v[68:71]
	v_mfma_f32_16x16x32_bf16 v[64:67], v[152:155], v[214:217], v[64:67]
	v_mfma_f32_16x16x32_bf16 v[116:119], v[148:151], v[194:197], v[116:119]
	v_mfma_f32_16x16x32_bf16 v[112:115], v[156:159], v[194:197], v[112:115]
	v_mfma_f32_16x16x32_bf16 v[100:103], v[148:151], v[202:205], v[100:103]
	v_mfma_f32_16x16x32_bf16 v[96:99], v[156:159], v[202:205], v[96:99]
	v_mfma_f32_16x16x32_bf16 v[84:87], v[148:151], v[210:213], v[84:87]
	v_mfma_f32_16x16x32_bf16 v[80:83], v[156:159], v[210:213], v[80:83]
	v_mfma_f32_16x16x32_bf16 v[68:71], v[148:151], v[218:221], v[68:71]
	v_mfma_f32_16x16x32_bf16 v[64:67], v[156:159], v[218:221], v[64:67]
	s_setprio 0
	s_barrier
	s_add_i32 s28, s36, s3
	v_lshl_add_u64 v[172:173], v[172:173], 0, s[18:19]
	s_mov_b32 m0, s28
	ds_read_b128 v[176:179], v190 offset:49152
	ds_read_b128 v[180:183], v190 offset:50176
	ds_read_b128 v[194:197], v190 offset:51200
	ds_read_b128 v[198:201], v190 offset:52224
	ds_read_b128 v[202:205], v190 offset:53248
	ds_read_b128 v[206:209], v190 offset:54272
	ds_read_b128 v[210:213], v190 offset:55296
	ds_read_b128 v[214:217], v190 offset:56320
	global_load_lds_dwordx4 v[172:173], off
	v_lshl_add_u64 v[172:173], v[222:223], 0, s[18:19]
	s_add_i32 m0, s28, 0x2000
	s_add_i32 s28, s37, s3
	global_load_lds_dwordx4 v[172:173], off
	v_lshl_add_u64 v[172:173], v[230:231], 0, s[18:19]
	s_mov_b32 m0, s28
	s_nop 0
	global_load_lds_dwordx4 v[172:173], off
	v_lshl_add_u64 v[172:173], v[232:233], 0, s[18:19]
	s_add_i32 m0, s28, 0x2000
	s_nop 0
	global_load_lds_dwordx4 v[172:173], off
	v_lshl_add_u64 v[172:173], v[234:235], 0, s[18:19]
	s_mov_b32 m0, s74
	s_nop 0
	global_load_lds_dwordx4 v[172:173], off
	v_lshl_add_u64 v[172:173], v[236:237], 0, s[18:19]
	s_mov_b32 m0, s75
	s_nop 0
	global_load_lds_dwordx4 v[172:173], off
	s_waitcnt vmcnt(8)
	s_waitcnt lgkmcnt(0)
	s_barrier
	s_setprio 1
	s_waitcnt lgkmcnt(0)
	v_mfma_f32_16x16x32_bf16 v[60:63], v[128:131], v[176:179], v[60:63]
	v_mfma_f32_16x16x32_bf16 v[56:59], v[136:139], v[176:179], v[56:59]
	v_mfma_f32_16x16x32_bf16 v[44:47], v[128:131], v[194:197], v[44:47]
	v_mfma_f32_16x16x32_bf16 v[40:43], v[136:139], v[194:197], v[40:43]
	v_mfma_f32_16x16x32_bf16 v[28:31], v[128:131], v[202:205], v[28:31]
	v_mfma_f32_16x16x32_bf16 v[24:27], v[136:139], v[202:205], v[24:27]
	v_mfma_f32_16x16x32_bf16 v[12:15], v[128:131], v[210:213], v[12:15]
	v_mfma_f32_16x16x32_bf16 v[8:11], v[136:139], v[210:213], v[8:11]
	v_mfma_f32_16x16x32_bf16 v[60:63], v[132:135], v[180:183], v[60:63]
	v_mfma_f32_16x16x32_bf16 v[56:59], v[140:143], v[180:183], v[56:59]
	v_mfma_f32_16x16x32_bf16 v[44:47], v[132:135], v[198:201], v[44:47]
	v_mfma_f32_16x16x32_bf16 v[40:43], v[140:143], v[198:201], v[40:43]
	v_mfma_f32_16x16x32_bf16 v[28:31], v[132:135], v[206:209], v[28:31]
	v_mfma_f32_16x16x32_bf16 v[24:27], v[140:143], v[206:209], v[24:27]
	v_mfma_f32_16x16x32_bf16 v[12:15], v[132:135], v[214:217], v[12:15]
	v_mfma_f32_16x16x32_bf16 v[8:11], v[140:143], v[214:217], v[8:11]
	s_setprio 0
	s_setprio 1
	v_mfma_f32_16x16x32_bf16 v[52:55], v[144:147], v[176:179], v[52:55]
	s_add_i32 s63, s63, 2
	v_mfma_f32_16x16x32_bf16 v[48:51], v[152:155], v[176:179], v[48:51]
	s_add_u32 s30, s30, 0x100
	v_mfma_f32_16x16x32_bf16 v[36:39], v[144:147], v[194:197], v[36:39]
	s_addc_u32 s31, s31, 0
	v_mfma_f32_16x16x32_bf16 v[32:35], v[152:155], v[194:197], v[32:35]
	s_cmpk_gt_u32 s63, 0x55
	v_mfma_f32_16x16x32_bf16 v[20:23], v[144:147], v[202:205], v[20:23]
	v_mfma_f32_16x16x32_bf16 v[16:19], v[152:155], v[202:205], v[16:19]
	v_mfma_f32_16x16x32_bf16 v[4:7], v[144:147], v[210:213], v[4:7]
	v_mfma_f32_16x16x32_bf16 v[0:3], v[152:155], v[210:213], v[0:3]
	v_mfma_f32_16x16x32_bf16 v[52:55], v[148:151], v[180:183], v[52:55]
	v_mfma_f32_16x16x32_bf16 v[48:51], v[156:159], v[180:183], v[48:51]
	v_mfma_f32_16x16x32_bf16 v[36:39], v[148:151], v[198:201], v[36:39]
	v_mfma_f32_16x16x32_bf16 v[32:35], v[156:159], v[198:201], v[32:35]
	v_mfma_f32_16x16x32_bf16 v[20:23], v[148:151], v[206:209], v[20:23]
	v_mfma_f32_16x16x32_bf16 v[16:19], v[156:159], v[206:209], v[16:19]
	v_mfma_f32_16x16x32_bf16 v[4:7], v[148:151], v[214:217], v[4:7]
	v_mfma_f32_16x16x32_bf16 v[0:3], v[156:159], v[214:217], v[0:3]
	s_setprio 0
	s_barrier
	s_cbranch_scc1 .LBB0_364
	v_mov_b32_e32 v172, v171
	v_mov_b32_e32 v160, v175
	v_mov_b32_e32 v174, v191
	v_mov_b32_e32 v170, v192
	s_mov_b64 s[28:29], s[34:35]
	s_branch .LBB0_360

.LBB0_454:
	ds_read_b128 v[146:149], v160
	ds_read_b128 v[150:153], v160 offset:1024
	ds_read_b128 v[154:157], v160 offset:2048
	ds_read_b128 v[166:169], v160 offset:3072
	ds_read_b128 v[170:173], v161
	ds_read_b128 v[174:177], v161 offset:1024
	ds_read_b128 v[178:181], v161 offset:2048
	ds_read_b128 v[182:185], v161 offset:3072
	s_add_u32 s38, s36, 0xfff80080
	s_addc_u32 s39, s37, -1
	s_cmp_eq_u32 s63, 28
	s_cselect_b32 s41, s9, s39
	s_cselect_b32 s40, s10, s38
	s_cselect_b32 s39, s25, s62
	s_cselect_b32 s38, s27, s35
	v_lshl_add_u64 v[218:219], s[36:37], 0, v[138:139]
	s_add_i32 m0, s60, 0xc000
	ds_read_b128 v[186:189], v162
	ds_read_b128 v[190:193], v162 offset:1024
	ds_read_b128 v[194:197], v162 offset:2048
	ds_read_b128 v[198:201], v162 offset:3072
	ds_read_b128 v[202:205], v162 offset:4096
	ds_read_b128 v[206:209], v162 offset:5120
	ds_read_b128 v[210:213], v162 offset:6144
	ds_read_b128 v[214:217], v162 offset:7168
	global_load_lds_dwordx4 v[218:219], off
	v_lshl_add_u64 v[218:219], s[36:37], 0, v[140:141]
	s_add_i32 m0, s60, 0xe000
	s_nop 0
	global_load_lds_dwordx4 v[218:219], off
	s_waitcnt vmcnt(8)
	s_waitcnt lgkmcnt(0)
	s_barrier
	s_setprio 1
	s_waitcnt lgkmcnt(0)
	v_mfma_f32_16x16x32_bf16 v[124:127], v[146:149], v[186:189], v[124:127]
	v_mfma_f32_16x16x32_bf16 v[120:123], v[154:157], v[186:189], v[120:123]
	v_mfma_f32_16x16x32_bf16 v[108:111], v[146:149], v[194:197], v[108:111]
	v_mfma_f32_16x16x32_bf16 v[104:107], v[154:157], v[194:197], v[104:107]
	v_mfma_f32_16x16x32_bf16 v[92:95], v[146:149], v[202:205], v[92:95]
	v_mfma_f32_16x16x32_bf16 v[88:91], v[154:157], v[202:205], v[88:91]
	v_mfma_f32_16x16x32_bf16 v[76:79], v[146:149], v[210:213], v[76:79]
	v_mfma_f32_16x16x32_bf16 v[72:75], v[154:157], v[210:213], v[72:75]
	v_mfma_f32_16x16x32_bf16 v[124:127], v[150:153], v[190:193], v[124:127]
	v_mfma_f32_16x16x32_bf16 v[120:123], v[166:169], v[190:193], v[120:123]
	v_mfma_f32_16x16x32_bf16 v[108:111], v[150:153], v[198:201], v[108:111]
	v_mfma_f32_16x16x32_bf16 v[104:107], v[166:169], v[198:201], v[104:107]
	v_mfma_f32_16x16x32_bf16 v[92:95], v[150:153], v[206:209], v[92:95]
	v_mfma_f32_16x16x32_bf16 v[88:91], v[166:169], v[206:209], v[88:91]
	v_mfma_f32_16x16x32_bf16 v[76:79], v[150:153], v[214:217], v[76:79]
	v_mfma_f32_16x16x32_bf16 v[72:75], v[166:169], v[214:217], v[72:75]
	s_setprio 0
	s_setprio 1
	v_mfma_f32_16x16x32_bf16 v[116:119], v[170:173], v[186:189], v[116:119]
	v_mfma_f32_16x16x32_bf16 v[112:115], v[178:181], v[186:189], v[112:115]
	v_mfma_f32_16x16x32_bf16 v[100:103], v[170:173], v[194:197], v[100:103]
	v_mfma_f32_16x16x32_bf16 v[96:99], v[178:181], v[194:197], v[96:99]
	v_mfma_f32_16x16x32_bf16 v[84:87], v[170:173], v[202:205], v[84:87]
	v_mfma_f32_16x16x32_bf16 v[80:83], v[178:181], v[202:205], v[80:83]
	v_mfma_f32_16x16x32_bf16 v[68:71], v[170:173], v[210:213], v[68:71]
	v_mfma_f32_16x16x32_bf16 v[64:67], v[178:181], v[210:213], v[64:67]
	v_mfma_f32_16x16x32_bf16 v[116:119], v[174:177], v[190:193], v[116:119]
	v_mfma_f32_16x16x32_bf16 v[112:115], v[182:185], v[190:193], v[112:115]
	v_mfma_f32_16x16x32_bf16 v[100:103], v[174:177], v[198:201], v[100:103]
	v_mfma_f32_16x16x32_bf16 v[96:99], v[182:185], v[198:201], v[96:99]
	v_mfma_f32_16x16x32_bf16 v[84:87], v[174:177], v[206:209], v[84:87]
	v_mfma_f32_16x16x32_bf16 v[80:83], v[182:185], v[206:209], v[80:83]
	v_mfma_f32_16x16x32_bf16 v[68:71], v[174:177], v[214:217], v[68:71]
	v_mfma_f32_16x16x32_bf16 v[64:67], v[182:185], v[214:217], v[64:67]
	s_setprio 0
	s_barrier
	s_add_i32 s84, s78, s3
	v_lshl_add_u64 v[218:219], s[38:39], 0, v[130:131]
	s_mov_b32 m0, s84
	ds_read_b128 v[186:189], v162 offset:16384
	ds_read_b128 v[190:193], v162 offset:17408
	ds_read_b128 v[194:197], v162 offset:18432
	ds_read_b128 v[198:201], v162 offset:19456
	ds_read_b128 v[202:205], v162 offset:20480
	ds_read_b128 v[206:209], v162 offset:21504
	ds_read_b128 v[210:213], v162 offset:22528
	ds_read_b128 v[214:217], v162 offset:23552
	global_load_lds_dwordx4 v[218:219], off
	s_add_i32 m0, s84, 0x2000
	s_add_u32 s84, s38, 0x80000
	v_lshl_add_u64 v[220:221], s[38:39], 0, v[134:135]
	s_addc_u32 s85, s39, 0
	s_add_i32 s89, s79, s3
	global_load_lds_dwordx4 v[220:221], off
	v_lshl_add_u64 v[222:223], s[84:85], 0, v[130:131]
	s_mov_b32 m0, s89
	v_lshl_add_u64 v[226:227], s[40:41], 0, v[132:133]
	global_load_lds_dwordx4 v[222:223], off
	v_lshl_add_u64 v[222:223], s[84:85], 0, v[134:135]
	s_add_i32 m0, s89, 0x2000
	s_nop 0
	global_load_lds_dwordx4 v[222:223], off
	v_lshl_add_u64 v[222:223], s[40:41], 0, v[128:129]
	s_mov_b32 m0, s60
	s_nop 0
	global_load_lds_dwordx4 v[222:223], off
	s_mov_b32 m0, s61
	s_nop 0
	global_load_lds_dwordx4 v[226:227], off
	s_waitcnt vmcnt(8)
	s_waitcnt lgkmcnt(0)
	s_barrier
	s_setprio 1
	s_waitcnt lgkmcnt(0)
	v_mfma_f32_16x16x32_bf16 v[60:63], v[146:149], v[186:189], v[60:63]
	v_mfma_f32_16x16x32_bf16 v[56:59], v[154:157], v[186:189], v[56:59]
	v_mfma_f32_16x16x32_bf16 v[44:47], v[146:149], v[194:197], v[44:47]
	v_mfma_f32_16x16x32_bf16 v[40:43], v[154:157], v[194:197], v[40:43]
	v_mfma_f32_16x16x32_bf16 v[28:31], v[146:149], v[202:205], v[28:31]
	v_mfma_f32_16x16x32_bf16 v[24:27], v[154:157], v[202:205], v[24:27]
	v_mfma_f32_16x16x32_bf16 v[12:15], v[146:149], v[210:213], v[12:15]
	v_mfma_f32_16x16x32_bf16 v[8:11], v[154:157], v[210:213], v[8:11]
	v_mfma_f32_16x16x32_bf16 v[60:63], v[150:153], v[190:193], v[60:63]
	v_mfma_f32_16x16x32_bf16 v[56:59], v[166:169], v[190:193], v[56:59]
	v_mfma_f32_16x16x32_bf16 v[44:47], v[150:153], v[198:201], v[44:47]
	v_mfma_f32_16x16x32_bf16 v[40:43], v[166:169], v[198:201], v[40:43]
	v_mfma_f32_16x16x32_bf16 v[28:31], v[150:153], v[206:209], v[28:31]
	v_mfma_f32_16x16x32_bf16 v[24:27], v[166:169], v[206:209], v[24:27]
	v_mfma_f32_16x16x32_bf16 v[12:15], v[150:153], v[214:217], v[12:15]
	v_mfma_f32_16x16x32_bf16 v[8:11], v[166:169], v[214:217], v[8:11]
	s_setprio 0
	s_setprio 1
	v_mfma_f32_16x16x32_bf16 v[52:55], v[170:173], v[186:189], v[52:55]
	v_mfma_f32_16x16x32_bf16 v[48:51], v[178:181], v[186:189], v[48:51]
	v_mfma_f32_16x16x32_bf16 v[36:39], v[170:173], v[194:197], v[36:39]
	v_mfma_f32_16x16x32_bf16 v[32:35], v[178:181], v[194:197], v[32:35]
	v_mfma_f32_16x16x32_bf16 v[20:23], v[170:173], v[202:205], v[20:23]
	v_mfma_f32_16x16x32_bf16 v[16:19], v[178:181], v[202:205], v[16:19]
	v_mfma_f32_16x16x32_bf16 v[4:7], v[170:173], v[210:213], v[4:7]
	v_mfma_f32_16x16x32_bf16 v[0:3], v[178:181], v[210:213], v[0:3]
	v_mfma_f32_16x16x32_bf16 v[52:55], v[174:177], v[190:193], v[52:55]
	v_mfma_f32_16x16x32_bf16 v[48:51], v[182:185], v[190:193], v[48:51]
	v_mfma_f32_16x16x32_bf16 v[36:39], v[174:177], v[198:201], v[36:39]
	v_mfma_f32_16x16x32_bf16 v[32:35], v[182:185], v[198:201], v[32:35]
	v_mfma_f32_16x16x32_bf16 v[20:23], v[174:177], v[206:209], v[20:23]
	v_mfma_f32_16x16x32_bf16 v[16:19], v[182:185], v[206:209], v[16:19]
	v_mfma_f32_16x16x32_bf16 v[4:7], v[174:177], v[214:217], v[4:7]
	v_mfma_f32_16x16x32_bf16 v[0:3], v[182:185], v[214:217], v[0:3]
	s_setprio 0
	s_barrier
	s_add_i32 s84, 0, 0x18000
	v_add_u32_e32 v165, s84, v159
	s_add_i32 s85, 0, 0x1c000
	ds_read_b128 v[146:149], v165
	ds_read_b128 v[150:153], v165 offset:1024
	ds_read_b128 v[154:157], v165 offset:2048
	ds_read_b128 v[166:169], v165 offset:3072
	v_add_u32_e32 v165, s85, v159
	ds_read_b128 v[170:173], v165
	ds_read_b128 v[174:177], v165 offset:1024
	ds_read_b128 v[178:181], v165 offset:2048
	ds_read_b128 v[182:185], v165 offset:3072
	s_add_u32 s40, s40, 0x80000
	s_addc_u32 s41, s41, 0
	s_mov_b32 m0, s69
	v_lshl_add_u64 v[228:229], s[40:41], 0, v[128:129]
	ds_read_b128 v[186:189], v162 offset:32768
	ds_read_b128 v[190:193], v162 offset:33792
	ds_read_b128 v[194:197], v162 offset:34816
	ds_read_b128 v[198:201], v162 offset:35840
	ds_read_b128 v[202:205], v162 offset:36864
	ds_read_b128 v[206:209], v162 offset:37888
	ds_read_b128 v[210:213], v162 offset:38912
	ds_read_b128 v[214:217], v162 offset:39936
	global_load_lds_dwordx4 v[228:229], off
	v_lshl_add_u64 v[228:229], s[40:41], 0, v[132:133]
	s_mov_b32 m0, s72
	s_nop 0
	global_load_lds_dwordx4 v[228:229], off
	s_waitcnt vmcnt(8)
	s_waitcnt lgkmcnt(0)
	s_barrier
	s_setprio 1
	s_waitcnt lgkmcnt(0)
	v_mfma_f32_16x16x32_bf16 v[124:127], v[146:149], v[186:189], v[124:127]
	v_mfma_f32_16x16x32_bf16 v[120:123], v[154:157], v[186:189], v[120:123]
	v_mfma_f32_16x16x32_bf16 v[108:111], v[146:149], v[194:197], v[108:111]
	v_mfma_f32_16x16x32_bf16 v[104:107], v[154:157], v[194:197], v[104:107]
	v_mfma_f32_16x16x32_bf16 v[92:95], v[146:149], v[202:205], v[92:95]
	v_mfma_f32_16x16x32_bf16 v[88:91], v[154:157], v[202:205], v[88:91]
	v_mfma_f32_16x16x32_bf16 v[76:79], v[146:149], v[210:213], v[76:79]
	v_mfma_f32_16x16x32_bf16 v[72:75], v[154:157], v[210:213], v[72:75]
	v_mfma_f32_16x16x32_bf16 v[124:127], v[150:153], v[190:193], v[124:127]
	v_mfma_f32_16x16x32_bf16 v[120:123], v[166:169], v[190:193], v[120:123]
	v_mfma_f32_16x16x32_bf16 v[108:111], v[150:153], v[198:201], v[108:111]
	v_mfma_f32_16x16x32_bf16 v[104:107], v[166:169], v[198:201], v[104:107]
	v_mfma_f32_16x16x32_bf16 v[92:95], v[150:153], v[206:209], v[92:95]
	v_mfma_f32_16x16x32_bf16 v[88:91], v[166:169], v[206:209], v[88:91]
	v_mfma_f32_16x16x32_bf16 v[76:79], v[150:153], v[214:217], v[76:79]
	v_mfma_f32_16x16x32_bf16 v[72:75], v[166:169], v[214:217], v[72:75]
	s_setprio 0
	s_setprio 1
	v_mfma_f32_16x16x32_bf16 v[116:119], v[170:173], v[186:189], v[116:119]
	v_mfma_f32_16x16x32_bf16 v[112:115], v[178:181], v[186:189], v[112:115]
	v_mfma_f32_16x16x32_bf16 v[100:103], v[170:173], v[194:197], v[100:103]
	v_mfma_f32_16x16x32_bf16 v[96:99], v[178:181], v[194:197], v[96:99]
	v_mfma_f32_16x16x32_bf16 v[84:87], v[170:173], v[202:205], v[84:87]
	v_mfma_f32_16x16x32_bf16 v[80:83], v[178:181], v[202:205], v[80:83]
	v_mfma_f32_16x16x32_bf16 v[68:71], v[170:173], v[210:213], v[68:71]
	v_mfma_f32_16x16x32_bf16 v[64:67], v[178:181], v[210:213], v[64:67]
	v_mfma_f32_16x16x32_bf16 v[116:119], v[174:177], v[190:193], v[116:119]
	v_mfma_f32_16x16x32_bf16 v[112:115], v[182:185], v[190:193], v[112:115]
	v_mfma_f32_16x16x32_bf16 v[100:103], v[174:177], v[198:201], v[100:103]
	v_mfma_f32_16x16x32_bf16 v[96:99], v[182:185], v[198:201], v[96:99]
	v_mfma_f32_16x16x32_bf16 v[84:87], v[174:177], v[206:209], v[84:87]
	v_mfma_f32_16x16x32_bf16 v[80:83], v[182:185], v[206:209], v[80:83]
	v_mfma_f32_16x16x32_bf16 v[68:71], v[174:177], v[214:217], v[68:71]
	v_mfma_f32_16x16x32_bf16 v[64:67], v[182:185], v[214:217], v[64:67]
	s_setprio 0
	s_barrier
	s_add_i32 s40, s84, s3
	v_lshl_add_u64 v[218:219], v[218:219], 0, s[18:19]
	s_mov_b32 m0, s40
	ds_read_b128 v[186:189], v162 offset:49152
	ds_read_b128 v[190:193], v162 offset:50176
	ds_read_b128 v[194:197], v162 offset:51200
	ds_read_b128 v[198:201], v162 offset:52224
	ds_read_b128 v[202:205], v162 offset:53248
	ds_read_b128 v[206:209], v162 offset:54272
	ds_read_b128 v[210:213], v162 offset:55296
	ds_read_b128 v[214:217], v162 offset:56320
	global_load_lds_dwordx4 v[218:219], off
	s_add_i32 m0, s40, 0x2000
	s_add_u32 s38, s38, 0x80080
	v_lshl_add_u64 v[218:219], v[220:221], 0, s[18:19]
	s_addc_u32 s39, s39, 0
	s_add_i32 s40, s85, s3
	global_load_lds_dwordx4 v[218:219], off
	v_lshl_add_u64 v[218:219], s[38:39], 0, v[130:131]
	s_mov_b32 m0, s40
	s_nop 0
	global_load_lds_dwordx4 v[218:219], off
	v_lshl_add_u64 v[218:219], s[38:39], 0, v[134:135]
	s_add_i32 m0, s40, 0x2000
	s_nop 0
	global_load_lds_dwordx4 v[218:219], off
	v_lshl_add_u64 v[218:219], v[222:223], 0, s[18:19]
	s_mov_b32 m0, s73
	s_nop 0
	global_load_lds_dwordx4 v[218:219], off
	v_lshl_add_u64 v[218:219], v[226:227], 0, s[18:19]
	s_mov_b32 m0, s74
	s_nop 0
	global_load_lds_dwordx4 v[218:219], off
	s_waitcnt vmcnt(8)
	s_waitcnt lgkmcnt(0)
	s_barrier
	s_setprio 1
	s_waitcnt lgkmcnt(0)
	v_mfma_f32_16x16x32_bf16 v[60:63], v[146:149], v[186:189], v[60:63]
	v_mfma_f32_16x16x32_bf16 v[56:59], v[154:157], v[186:189], v[56:59]
	v_mfma_f32_16x16x32_bf16 v[44:47], v[146:149], v[194:197], v[44:47]
	v_mfma_f32_16x16x32_bf16 v[40:43], v[154:157], v[194:197], v[40:43]
	v_mfma_f32_16x16x32_bf16 v[28:31], v[146:149], v[202:205], v[28:31]
	v_mfma_f32_16x16x32_bf16 v[24:27], v[154:157], v[202:205], v[24:27]
	v_mfma_f32_16x16x32_bf16 v[12:15], v[146:149], v[210:213], v[12:15]
	v_mfma_f32_16x16x32_bf16 v[8:11], v[154:157], v[210:213], v[8:11]
	v_mfma_f32_16x16x32_bf16 v[60:63], v[150:153], v[190:193], v[60:63]
	v_mfma_f32_16x16x32_bf16 v[56:59], v[166:169], v[190:193], v[56:59]
	v_mfma_f32_16x16x32_bf16 v[44:47], v[150:153], v[198:201], v[44:47]
	v_mfma_f32_16x16x32_bf16 v[40:43], v[166:169], v[198:201], v[40:43]
	v_mfma_f32_16x16x32_bf16 v[28:31], v[150:153], v[206:209], v[28:31]
	v_mfma_f32_16x16x32_bf16 v[24:27], v[166:169], v[206:209], v[24:27]
	v_mfma_f32_16x16x32_bf16 v[12:15], v[150:153], v[214:217], v[12:15]
	v_mfma_f32_16x16x32_bf16 v[8:11], v[166:169], v[214:217], v[8:11]
	s_setprio 0
	s_setprio 1
	v_mfma_f32_16x16x32_bf16 v[52:55], v[170:173], v[186:189], v[52:55]
	s_add_i32 s63, s63, 2
	v_mfma_f32_16x16x32_bf16 v[48:51], v[178:181], v[186:189], v[48:51]
	s_add_u32 s36, s36, 0x100
	v_mfma_f32_16x16x32_bf16 v[36:39], v[170:173], v[194:197], v[36:39]
	s_addc_u32 s37, s37, 0
	v_mfma_f32_16x16x32_bf16 v[32:35], v[178:181], v[194:197], v[32:35]
	s_add_u32 s35, s35, 0x100
	v_mfma_f32_16x16x32_bf16 v[20:23], v[170:173], v[202:205], v[20:23]
	s_addc_u32 s62, s62, 0
	v_mfma_f32_16x16x32_bf16 v[16:19], v[178:181], v[202:205], v[16:19]
	s_cmp_gt_u32 s63, 29
	v_mfma_f32_16x16x32_bf16 v[4:7], v[170:173], v[210:213], v[4:7]
	v_mfma_f32_16x16x32_bf16 v[0:3], v[178:181], v[210:213], v[0:3]
	v_mfma_f32_16x16x32_bf16 v[52:55], v[174:177], v[190:193], v[52:55]
	v_mfma_f32_16x16x32_bf16 v[48:51], v[182:185], v[190:193], v[48:51]
	v_mfma_f32_16x16x32_bf16 v[36:39], v[174:177], v[198:201], v[36:39]
	v_mfma_f32_16x16x32_bf16 v[32:35], v[182:185], v[198:201], v[32:35]
	v_mfma_f32_16x16x32_bf16 v[20:23], v[174:177], v[206:209], v[20:23]
	v_mfma_f32_16x16x32_bf16 v[16:19], v[182:185], v[206:209], v[16:19]
	v_mfma_f32_16x16x32_bf16 v[4:7], v[174:177], v[214:217], v[4:7]
	v_mfma_f32_16x16x32_bf16 v[0:3], v[182:185], v[214:217], v[0:3]
	s_setprio 0
	s_barrier
	s_cbranch_scc0 .LBB0_454
	s_and_b64 vcc, exec, s[20:21]
	s_cbranch_vccz .LBB0_457
	s_barrier

.LBB0_542:
	ds_read_b128 v[128:131], v167
	ds_read_b128 v[148:151], v167 offset:1024
	ds_read_b128 v[152:155], v167 offset:2048
	ds_read_b128 v[156:159], v167 offset:3072
	ds_read_b128 v[160:163], v168
	ds_read_b128 v[170:173], v168 offset:1024
	ds_read_b128 v[174:177], v168 offset:2048
	ds_read_b128 v[178:181], v168 offset:3072
	s_add_u32 s36, s8, 0xfff80080
	s_addc_u32 s37, s9, -1
	s_cmp_eq_u32 s81, 28
	s_cselect_b32 s39, s27, s37
	s_cselect_b32 s38, s62, s36
	s_cselect_b32 s37, s25, s80
	s_cselect_b32 s36, s63, s79
	v_lshl_add_u64 v[214:215], s[8:9], 0, v[140:141]
	s_add_i32 m0, s35, 0xc000
	ds_read_b128 v[182:185], v169
	ds_read_b128 v[186:189], v169 offset:1024
	ds_read_b128 v[190:193], v169 offset:2048
	ds_read_b128 v[194:197], v169 offset:3072
	ds_read_b128 v[198:201], v169 offset:4096
	ds_read_b128 v[202:205], v169 offset:5120
	ds_read_b128 v[206:209], v169 offset:6144
	ds_read_b128 v[210:213], v169 offset:7168
	global_load_lds_dwordx4 v[214:215], off
	v_lshl_add_u64 v[214:215], s[8:9], 0, v[142:143]
	s_add_i32 m0, s35, 0xe000
	s_nop 0
	global_load_lds_dwordx4 v[214:215], off
	s_waitcnt vmcnt(8)
	s_waitcnt lgkmcnt(0)
	s_barrier
	s_setprio 1
	s_waitcnt lgkmcnt(0)
	v_mfma_f32_16x16x32_bf16 v[124:127], v[128:131], v[182:185], v[124:127]
	v_mfma_f32_16x16x32_bf16 v[120:123], v[152:155], v[182:185], v[120:123]
	v_mfma_f32_16x16x32_bf16 v[112:115], v[128:131], v[190:193], v[112:115]
	v_mfma_f32_16x16x32_bf16 v[104:107], v[152:155], v[190:193], v[104:107]
	v_mfma_f32_16x16x32_bf16 v[96:99], v[128:131], v[198:201], v[96:99]
	v_mfma_f32_16x16x32_bf16 v[88:91], v[152:155], v[198:201], v[88:91]
	v_mfma_f32_16x16x32_bf16 v[80:83], v[128:131], v[206:209], v[80:83]
	v_mfma_f32_16x16x32_bf16 v[72:75], v[152:155], v[206:209], v[72:75]
	v_mfma_f32_16x16x32_bf16 v[124:127], v[148:151], v[186:189], v[124:127]
	v_mfma_f32_16x16x32_bf16 v[120:123], v[156:159], v[186:189], v[120:123]
	v_mfma_f32_16x16x32_bf16 v[112:115], v[148:151], v[194:197], v[112:115]
	v_mfma_f32_16x16x32_bf16 v[104:107], v[156:159], v[194:197], v[104:107]
	v_mfma_f32_16x16x32_bf16 v[96:99], v[148:151], v[202:205], v[96:99]
	v_mfma_f32_16x16x32_bf16 v[88:91], v[156:159], v[202:205], v[88:91]
	v_mfma_f32_16x16x32_bf16 v[80:83], v[148:151], v[210:213], v[80:83]
	v_mfma_f32_16x16x32_bf16 v[72:75], v[156:159], v[210:213], v[72:75]
	s_setprio 0
	s_setprio 1
	v_mfma_f32_16x16x32_bf16 v[116:119], v[160:163], v[182:185], v[116:119]
	v_mfma_f32_16x16x32_bf16 v[108:111], v[174:177], v[182:185], v[108:111]
	v_mfma_f32_16x16x32_bf16 v[100:103], v[160:163], v[190:193], v[100:103]
	v_mfma_f32_16x16x32_bf16 v[92:95], v[174:177], v[190:193], v[92:95]
	v_mfma_f32_16x16x32_bf16 v[84:87], v[160:163], v[198:201], v[84:87]
	v_mfma_f32_16x16x32_bf16 v[76:79], v[174:177], v[198:201], v[76:79]
	v_mfma_f32_16x16x32_bf16 v[68:71], v[160:163], v[206:209], v[68:71]
	v_mfma_f32_16x16x32_bf16 v[64:67], v[174:177], v[206:209], v[64:67]
	v_mfma_f32_16x16x32_bf16 v[116:119], v[170:173], v[186:189], v[116:119]
	v_mfma_f32_16x16x32_bf16 v[108:111], v[178:181], v[186:189], v[108:111]
	v_mfma_f32_16x16x32_bf16 v[100:103], v[170:173], v[194:197], v[100:103]
	v_mfma_f32_16x16x32_bf16 v[92:95], v[178:181], v[194:197], v[92:95]
	v_mfma_f32_16x16x32_bf16 v[84:87], v[170:173], v[202:205], v[84:87]
	v_mfma_f32_16x16x32_bf16 v[76:79], v[178:181], v[202:205], v[76:79]
	v_mfma_f32_16x16x32_bf16 v[68:71], v[170:173], v[210:213], v[68:71]
	v_mfma_f32_16x16x32_bf16 v[64:67], v[178:181], v[210:213], v[64:67]
	s_setprio 0
	s_barrier
	s_add_i32 s83, s75, s3
	v_lshl_add_u64 v[214:215], s[36:37], 0, v[134:135]
	s_mov_b32 m0, s83
	ds_read_b128 v[182:185], v169 offset:16384
	ds_read_b128 v[186:189], v169 offset:17408
	ds_read_b128 v[190:193], v169 offset:18432
	ds_read_b128 v[194:197], v169 offset:19456
	ds_read_b128 v[198:201], v169 offset:20480
	ds_read_b128 v[202:205], v169 offset:21504
	ds_read_b128 v[206:209], v169 offset:22528
	ds_read_b128 v[210:213], v169 offset:23552
	global_load_lds_dwordx4 v[214:215], off
	s_add_i32 m0, s83, 0x2000
	s_add_u32 s84, s36, 0x80000
	v_lshl_add_u64 v[216:217], s[36:37], 0, v[138:139]
	s_addc_u32 s85, s37, 0
	s_add_i32 s83, s76, s3
	global_load_lds_dwordx4 v[216:217], off
	v_lshl_add_u64 v[218:219], s[84:85], 0, v[134:135]
	s_mov_b32 m0, s83
	v_lshl_add_u64 v[220:221], s[38:39], 0, v[136:137]
	global_load_lds_dwordx4 v[218:219], off
	v_lshl_add_u64 v[218:219], s[84:85], 0, v[138:139]
	s_add_i32 m0, s83, 0x2000
	s_nop 0
	global_load_lds_dwordx4 v[218:219], off
	v_lshl_add_u64 v[218:219], s[38:39], 0, v[132:133]
	s_mov_b32 m0, s35
	s_nop 0
	global_load_lds_dwordx4 v[218:219], off
	s_mov_b32 m0, s41
	s_nop 0
	global_load_lds_dwordx4 v[220:221], off
	s_waitcnt vmcnt(8)
	s_waitcnt lgkmcnt(0)
	s_barrier
	s_setprio 1
	s_waitcnt lgkmcnt(0)
	v_mfma_f32_16x16x32_bf16 v[60:63], v[128:131], v[182:185], v[60:63]
	v_mfma_f32_16x16x32_bf16 v[56:59], v[152:155], v[182:185], v[56:59]
	v_mfma_f32_16x16x32_bf16 v[48:51], v[128:131], v[190:193], v[48:51]
	v_mfma_f32_16x16x32_bf16 v[40:43], v[152:155], v[190:193], v[40:43]
	v_mfma_f32_16x16x32_bf16 v[32:35], v[128:131], v[198:201], v[32:35]
	v_mfma_f32_16x16x32_bf16 v[24:27], v[152:155], v[198:201], v[24:27]
	v_mfma_f32_16x16x32_bf16 v[16:19], v[128:131], v[206:209], v[16:19]
	v_mfma_f32_16x16x32_bf16 v[8:11], v[152:155], v[206:209], v[8:11]
	v_mfma_f32_16x16x32_bf16 v[60:63], v[148:151], v[186:189], v[60:63]
	v_mfma_f32_16x16x32_bf16 v[56:59], v[156:159], v[186:189], v[56:59]
	v_mfma_f32_16x16x32_bf16 v[48:51], v[148:151], v[194:197], v[48:51]
	v_mfma_f32_16x16x32_bf16 v[40:43], v[156:159], v[194:197], v[40:43]
	v_mfma_f32_16x16x32_bf16 v[32:35], v[148:151], v[202:205], v[32:35]
	v_mfma_f32_16x16x32_bf16 v[24:27], v[156:159], v[202:205], v[24:27]
	v_mfma_f32_16x16x32_bf16 v[16:19], v[148:151], v[210:213], v[16:19]
	v_mfma_f32_16x16x32_bf16 v[8:11], v[156:159], v[210:213], v[8:11]
	s_setprio 0
	s_setprio 1
	v_mfma_f32_16x16x32_bf16 v[52:55], v[160:163], v[182:185], v[52:55]
	v_mfma_f32_16x16x32_bf16 v[44:47], v[174:177], v[182:185], v[44:47]
	v_mfma_f32_16x16x32_bf16 v[36:39], v[160:163], v[190:193], v[36:39]
	v_mfma_f32_16x16x32_bf16 v[28:31], v[174:177], v[190:193], v[28:31]
	v_mfma_f32_16x16x32_bf16 v[20:23], v[160:163], v[198:201], v[20:23]
	v_mfma_f32_16x16x32_bf16 v[12:15], v[174:177], v[198:201], v[12:15]
	v_mfma_f32_16x16x32_bf16 v[4:7], v[160:163], v[206:209], v[4:7]
	v_mfma_f32_16x16x32_bf16 v[0:3], v[174:177], v[206:209], v[0:3]
	v_mfma_f32_16x16x32_bf16 v[52:55], v[170:173], v[186:189], v[52:55]
	v_mfma_f32_16x16x32_bf16 v[44:47], v[178:181], v[186:189], v[44:47]
	v_mfma_f32_16x16x32_bf16 v[36:39], v[170:173], v[194:197], v[36:39]
	v_mfma_f32_16x16x32_bf16 v[28:31], v[178:181], v[194:197], v[28:31]
	v_mfma_f32_16x16x32_bf16 v[20:23], v[170:173], v[202:205], v[20:23]
	v_mfma_f32_16x16x32_bf16 v[12:15], v[178:181], v[202:205], v[12:15]
	v_mfma_f32_16x16x32_bf16 v[4:7], v[170:173], v[210:213], v[4:7]
	v_mfma_f32_16x16x32_bf16 v[0:3], v[178:181], v[210:213], v[0:3]
	s_setprio 0
	s_barrier
	s_add_i32 s83, 0, 0x18000
	s_add_i32 s84, 0, 0x1c000
	v_add_u32_e32 v156, s83, v165
	v_add_u32_e32 v178, s84, v165
	ds_read_b128 v[128:131], v156
	ds_read_b128 v[148:151], v156 offset:1024
	ds_read_b128 v[152:155], v156 offset:2048
	ds_read_b128 v[156:159], v156 offset:3072
	ds_read_b128 v[160:163], v178
	ds_read_b128 v[170:173], v178 offset:1024
	ds_read_b128 v[174:177], v178 offset:2048
	ds_read_b128 v[178:181], v178 offset:3072
	s_add_u32 s38, s38, 0x80000
	s_addc_u32 s39, s39, 0
	s_mov_b32 m0, s44
	v_lshl_add_u64 v[222:223], s[38:39], 0, v[132:133]
	ds_read_b128 v[182:185], v169 offset:32768
	ds_read_b128 v[186:189], v169 offset:33792
	ds_read_b128 v[190:193], v169 offset:34816
	ds_read_b128 v[194:197], v169 offset:35840
	ds_read_b128 v[198:201], v169 offset:36864
	ds_read_b128 v[202:205], v169 offset:37888
	ds_read_b128 v[206:209], v169 offset:38912
	ds_read_b128 v[210:213], v169 offset:39936
	global_load_lds_dwordx4 v[222:223], off
	v_lshl_add_u64 v[222:223], s[38:39], 0, v[136:137]
	s_mov_b32 m0, s45
	s_nop 0
	global_load_lds_dwordx4 v[222:223], off
	s_waitcnt vmcnt(8)
	s_waitcnt lgkmcnt(0)
	s_barrier
	s_setprio 1
	s_waitcnt lgkmcnt(0)
	v_mfma_f32_16x16x32_bf16 v[124:127], v[128:131], v[182:185], v[124:127]
	v_mfma_f32_16x16x32_bf16 v[120:123], v[152:155], v[182:185], v[120:123]
	v_mfma_f32_16x16x32_bf16 v[112:115], v[128:131], v[190:193], v[112:115]
	v_mfma_f32_16x16x32_bf16 v[104:107], v[152:155], v[190:193], v[104:107]
	v_mfma_f32_16x16x32_bf16 v[96:99], v[128:131], v[198:201], v[96:99]
	v_mfma_f32_16x16x32_bf16 v[88:91], v[152:155], v[198:201], v[88:91]
	v_mfma_f32_16x16x32_bf16 v[80:83], v[128:131], v[206:209], v[80:83]
	v_mfma_f32_16x16x32_bf16 v[72:75], v[152:155], v[206:209], v[72:75]
	v_mfma_f32_16x16x32_bf16 v[124:127], v[148:151], v[186:189], v[124:127]
	v_mfma_f32_16x16x32_bf16 v[120:123], v[156:159], v[186:189], v[120:123]
	v_mfma_f32_16x16x32_bf16 v[112:115], v[148:151], v[194:197], v[112:115]
	v_mfma_f32_16x16x32_bf16 v[104:107], v[156:159], v[194:197], v[104:107]
	v_mfma_f32_16x16x32_bf16 v[96:99], v[148:151], v[202:205], v[96:99]
	v_mfma_f32_16x16x32_bf16 v[88:91], v[156:159], v[202:205], v[88:91]
	v_mfma_f32_16x16x32_bf16 v[80:83], v[148:151], v[210:213], v[80:83]
	v_mfma_f32_16x16x32_bf16 v[72:75], v[156:159], v[210:213], v[72:75]
	s_setprio 0
	s_setprio 1
	v_mfma_f32_16x16x32_bf16 v[116:119], v[160:163], v[182:185], v[116:119]
	v_mfma_f32_16x16x32_bf16 v[108:111], v[174:177], v[182:185], v[108:111]
	v_mfma_f32_16x16x32_bf16 v[100:103], v[160:163], v[190:193], v[100:103]
	v_mfma_f32_16x16x32_bf16 v[92:95], v[174:177], v[190:193], v[92:95]
	v_mfma_f32_16x16x32_bf16 v[84:87], v[160:163], v[198:201], v[84:87]
	v_mfma_f32_16x16x32_bf16 v[76:79], v[174:177], v[198:201], v[76:79]
	v_mfma_f32_16x16x32_bf16 v[68:71], v[160:163], v[206:209], v[68:71]
	v_mfma_f32_16x16x32_bf16 v[64:67], v[174:177], v[206:209], v[64:67]
	v_mfma_f32_16x16x32_bf16 v[116:119], v[170:173], v[186:189], v[116:119]
	v_mfma_f32_16x16x32_bf16 v[108:111], v[178:181], v[186:189], v[108:111]
	v_mfma_f32_16x16x32_bf16 v[100:103], v[170:173], v[194:197], v[100:103]
	v_mfma_f32_16x16x32_bf16 v[92:95], v[178:181], v[194:197], v[92:95]
	v_mfma_f32_16x16x32_bf16 v[84:87], v[170:173], v[202:205], v[84:87]
	v_mfma_f32_16x16x32_bf16 v[76:79], v[178:181], v[202:205], v[76:79]
	v_mfma_f32_16x16x32_bf16 v[68:71], v[170:173], v[210:213], v[68:71]
	v_mfma_f32_16x16x32_bf16 v[64:67], v[178:181], v[210:213], v[64:67]
	s_setprio 0
	s_barrier
	s_add_i32 s38, s83, s3
	v_lshl_add_u64 v[214:215], v[214:215], 0, s[16:17]
	s_mov_b32 m0, s38
	ds_read_b128 v[182:185], v169 offset:49152
	ds_read_b128 v[186:189], v169 offset:50176
	ds_read_b128 v[190:193], v169 offset:51200
	ds_read_b128 v[194:197], v169 offset:52224
	ds_read_b128 v[198:201], v169 offset:53248
	ds_read_b128 v[202:205], v169 offset:54272
	ds_read_b128 v[206:209], v169 offset:55296
	ds_read_b128 v[210:213], v169 offset:56320
	global_load_lds_dwordx4 v[214:215], off
	s_add_i32 m0, s38, 0x2000
	s_add_u32 s36, s36, 0x80080
	v_lshl_add_u64 v[214:215], v[216:217], 0, s[16:17]
	s_addc_u32 s37, s37, 0
	s_add_i32 s38, s84, s3
	global_load_lds_dwordx4 v[214:215], off
	v_lshl_add_u64 v[214:215], s[36:37], 0, v[134:135]
	s_mov_b32 m0, s38
	s_nop 0
	global_load_lds_dwordx4 v[214:215], off
	v_lshl_add_u64 v[214:215], s[36:37], 0, v[138:139]
	s_add_i32 m0, s38, 0x2000
	s_nop 0
	global_load_lds_dwordx4 v[214:215], off
	v_lshl_add_u64 v[214:215], v[218:219], 0, s[16:17]
	s_mov_b32 m0, s61
	s_nop 0
	global_load_lds_dwordx4 v[214:215], off
	v_lshl_add_u64 v[214:215], v[220:221], 0, s[16:17]
	s_mov_b32 m0, s67
	s_nop 0
	global_load_lds_dwordx4 v[214:215], off
	s_waitcnt vmcnt(8)
	s_waitcnt lgkmcnt(0)
	s_barrier
	s_setprio 1
	s_waitcnt lgkmcnt(0)
	v_mfma_f32_16x16x32_bf16 v[60:63], v[128:131], v[182:185], v[60:63]
	v_mfma_f32_16x16x32_bf16 v[56:59], v[152:155], v[182:185], v[56:59]
	v_mfma_f32_16x16x32_bf16 v[48:51], v[128:131], v[190:193], v[48:51]
	v_mfma_f32_16x16x32_bf16 v[40:43], v[152:155], v[190:193], v[40:43]
	v_mfma_f32_16x16x32_bf16 v[32:35], v[128:131], v[198:201], v[32:35]
	v_mfma_f32_16x16x32_bf16 v[24:27], v[152:155], v[198:201], v[24:27]
	v_mfma_f32_16x16x32_bf16 v[16:19], v[128:131], v[206:209], v[16:19]
	v_mfma_f32_16x16x32_bf16 v[8:11], v[152:155], v[206:209], v[8:11]
	v_mfma_f32_16x16x32_bf16 v[60:63], v[148:151], v[186:189], v[60:63]
	v_mfma_f32_16x16x32_bf16 v[56:59], v[156:159], v[186:189], v[56:59]
	v_mfma_f32_16x16x32_bf16 v[48:51], v[148:151], v[194:197], v[48:51]
	v_mfma_f32_16x16x32_bf16 v[40:43], v[156:159], v[194:197], v[40:43]
	v_mfma_f32_16x16x32_bf16 v[32:35], v[148:151], v[202:205], v[32:35]
	v_mfma_f32_16x16x32_bf16 v[24:27], v[156:159], v[202:205], v[24:27]
	v_mfma_f32_16x16x32_bf16 v[16:19], v[148:151], v[210:213], v[16:19]
	v_mfma_f32_16x16x32_bf16 v[8:11], v[156:159], v[210:213], v[8:11]
	s_setprio 0
	s_setprio 1
	v_mfma_f32_16x16x32_bf16 v[52:55], v[160:163], v[182:185], v[52:55]
	s_add_i32 s81, s81, 2
	v_mfma_f32_16x16x32_bf16 v[44:47], v[174:177], v[182:185], v[44:47]
	s_add_u32 s8, s8, 0x100
	v_mfma_f32_16x16x32_bf16 v[36:39], v[160:163], v[190:193], v[36:39]
	s_addc_u32 s9, s9, 0
	v_mfma_f32_16x16x32_bf16 v[28:31], v[174:177], v[190:193], v[28:31]
	s_add_u32 s79, s79, 0x100
	v_mfma_f32_16x16x32_bf16 v[20:23], v[160:163], v[198:201], v[20:23]
	s_addc_u32 s80, s80, 0
	v_mfma_f32_16x16x32_bf16 v[12:15], v[174:177], v[198:201], v[12:15]
	s_cmp_gt_u32 s81, 29
	v_mfma_f32_16x16x32_bf16 v[4:7], v[160:163], v[206:209], v[4:7]
	v_mfma_f32_16x16x32_bf16 v[0:3], v[174:177], v[206:209], v[0:3]
	v_mfma_f32_16x16x32_bf16 v[52:55], v[170:173], v[186:189], v[52:55]
	v_mfma_f32_16x16x32_bf16 v[44:47], v[178:181], v[186:189], v[44:47]
	v_mfma_f32_16x16x32_bf16 v[36:39], v[170:173], v[194:197], v[36:39]
	v_mfma_f32_16x16x32_bf16 v[28:31], v[178:181], v[194:197], v[28:31]
	v_mfma_f32_16x16x32_bf16 v[20:23], v[170:173], v[202:205], v[20:23]
	v_mfma_f32_16x16x32_bf16 v[12:15], v[178:181], v[202:205], v[12:15]
	v_mfma_f32_16x16x32_bf16 v[4:7], v[170:173], v[210:213], v[4:7]
	v_mfma_f32_16x16x32_bf16 v[0:3], v[178:181], v[210:213], v[0:3]
	s_setprio 0
	s_barrier
	s_cbranch_scc0 .LBB0_542
	s_and_b64 vcc, exec, s[18:19]
	s_cbranch_vccz .LBB0_545
	s_barrier

.LBB0_950:
	s_add_u32 s40, s34, s36
	s_addc_u32 s41, s35, s37
	s_add_u32 s80, s40, 0x100
	s_addc_u32 s81, s41, 0
	s_and_b64 s[40:41], s[38:39], exec
	s_cselect_b32 s41, s81, s27
	s_cselect_b32 s40, s80, s29
	s_add_u32 s80, s63, s36
	s_addc_u32 s81, s76, s37
	s_and_b64 s[38:39], s[38:39], exec
	s_cselect_b32 s39, s81, s77
	s_cselect_b32 s38, s80, s78
	s_mov_b32 m0, s61
	v_lshl_add_u64 v[180:181], s[38:39], 0, v[186:187]
	s_add_u32 s80, s38, 0x80000
	ds_read_b128 v[132:135], v195 offset:16384
	ds_read_b128 v[198:201], v195 offset:17408
	ds_read_b128 v[202:205], v195 offset:18432
	ds_read_b128 v[206:209], v195 offset:19456
	ds_read_b128 v[210:213], v195 offset:20480
	ds_read_b128 v[214:217], v195 offset:21504
	ds_read_b128 v[218:221], v195 offset:22528
	ds_read_b128 v[226:229], v195 offset:23552
	global_load_lds_dwordx4 v[180:181], off
	v_lshl_add_u64 v[222:223], s[38:39], 0, v[184:185]
	s_mov_b32 m0, s64
	s_addc_u32 s81, s39, 0
	global_load_lds_dwordx4 v[222:223], off
	v_lshl_add_u64 v[230:231], s[80:81], 0, v[186:187]
	s_mov_b32 m0, s65
	v_lshl_add_u64 v[234:235], s[40:41], 0, v[130:131]
	global_load_lds_dwordx4 v[230:231], off
	v_lshl_add_u64 v[230:231], s[80:81], 0, v[184:185]
	s_mov_b32 m0, s66
	v_lshl_add_u64 v[236:237], s[40:41], 0, v[128:129]
	global_load_lds_dwordx4 v[230:231], off
	s_mov_b32 m0, s15
	s_nop 0
	global_load_lds_dwordx4 v[234:235], off
	s_mov_b32 m0, s67
	s_nop 0
	global_load_lds_dwordx4 v[236:237], off
	s_waitcnt vmcnt(8)
	s_waitcnt lgkmcnt(0)
	s_barrier
	s_setprio 1
	s_waitcnt lgkmcnt(0)
	v_mfma_f32_16x16x32_bf16 v[60:63], v[152:155], v[132:135], v[60:63]
	v_mfma_f32_16x16x32_bf16 v[56:59], v[160:163], v[132:135], v[56:59]
	v_mfma_f32_16x16x32_bf16 v[44:47], v[152:155], v[202:205], v[44:47]
	v_mfma_f32_16x16x32_bf16 v[40:43], v[160:163], v[202:205], v[40:43]
	v_mfma_f32_16x16x32_bf16 v[28:31], v[152:155], v[210:213], v[28:31]
	v_mfma_f32_16x16x32_bf16 v[24:27], v[160:163], v[210:213], v[24:27]
	v_mfma_f32_16x16x32_bf16 v[12:15], v[152:155], v[218:221], v[12:15]
	v_mfma_f32_16x16x32_bf16 v[8:11], v[160:163], v[218:221], v[8:11]
	v_mfma_f32_16x16x32_bf16 v[60:63], v[156:159], v[198:201], v[60:63]
	v_mfma_f32_16x16x32_bf16 v[56:59], v[164:167], v[198:201], v[56:59]
	v_mfma_f32_16x16x32_bf16 v[44:47], v[156:159], v[206:209], v[44:47]
	v_mfma_f32_16x16x32_bf16 v[40:43], v[164:167], v[206:209], v[40:43]
	v_mfma_f32_16x16x32_bf16 v[28:31], v[156:159], v[214:217], v[28:31]
	v_mfma_f32_16x16x32_bf16 v[24:27], v[164:167], v[214:217], v[24:27]
	v_mfma_f32_16x16x32_bf16 v[12:15], v[156:159], v[226:229], v[12:15]
	v_mfma_f32_16x16x32_bf16 v[8:11], v[164:167], v[226:229], v[8:11]
	s_setprio 0
	s_setprio 1
	v_mfma_f32_16x16x32_bf16 v[52:55], v[136:139], v[132:135], v[52:55]
	v_mfma_f32_16x16x32_bf16 v[48:51], v[144:147], v[132:135], v[48:51]
	v_mfma_f32_16x16x32_bf16 v[36:39], v[136:139], v[202:205], v[36:39]
	v_mfma_f32_16x16x32_bf16 v[32:35], v[144:147], v[202:205], v[32:35]
	v_mfma_f32_16x16x32_bf16 v[20:23], v[136:139], v[210:213], v[20:23]
	v_mfma_f32_16x16x32_bf16 v[16:19], v[144:147], v[210:213], v[16:19]
	v_mfma_f32_16x16x32_bf16 v[4:7], v[136:139], v[218:221], v[4:7]
	v_mfma_f32_16x16x32_bf16 v[0:3], v[144:147], v[218:221], v[0:3]
	v_mfma_f32_16x16x32_bf16 v[52:55], v[140:143], v[198:201], v[52:55]
	v_mfma_f32_16x16x32_bf16 v[48:51], v[148:151], v[198:201], v[48:51]
	v_mfma_f32_16x16x32_bf16 v[36:39], v[140:143], v[206:209], v[36:39]
	v_mfma_f32_16x16x32_bf16 v[32:35], v[148:151], v[206:209], v[32:35]
	v_mfma_f32_16x16x32_bf16 v[20:23], v[140:143], v[214:217], v[20:23]
	v_mfma_f32_16x16x32_bf16 v[16:19], v[148:151], v[214:217], v[16:19]
	v_mfma_f32_16x16x32_bf16 v[4:7], v[140:143], v[226:229], v[4:7]
	v_mfma_f32_16x16x32_bf16 v[0:3], v[148:151], v[226:229], v[0:3]
	s_setprio 0
	s_barrier
	s_add_i32 s80, 0, 0x18000
	v_add_u32_e32 v132, s80, v194
	s_add_i32 s81, 0, 0x1c000
	ds_read_b128 v[136:139], v132
	ds_read_b128 v[140:143], v132 offset:1024
	ds_read_b128 v[144:147], v132 offset:2048
	ds_read_b128 v[148:151], v132 offset:3072
	v_add_u32_e32 v132, s81, v194
	ds_read_b128 v[152:155], v132
	ds_read_b128 v[156:159], v132 offset:1024
	ds_read_b128 v[160:163], v132 offset:2048
	ds_read_b128 v[164:167], v132 offset:3072
	s_add_u32 s40, s40, 0x80000
	s_addc_u32 s41, s41, 0
	s_mov_b32 m0, s68
	v_lshl_add_u64 v[130:131], s[40:41], 0, v[130:131]
	ds_read_b128 v[198:201], v195 offset:32768
	ds_read_b128 v[202:205], v195 offset:33792
	ds_read_b128 v[206:209], v195 offset:34816
	ds_read_b128 v[210:213], v195 offset:35840
	ds_read_b128 v[214:217], v195 offset:36864
	ds_read_b128 v[218:221], v195 offset:37888
	ds_read_b128 v[226:229], v195 offset:38912
	ds_read_b128 v[230:233], v195 offset:39936
	global_load_lds_dwordx4 v[130:131], off
	v_lshl_add_u64 v[128:129], s[40:41], 0, v[128:129]
	s_mov_b32 m0, s69
	s_nop 0
	global_load_lds_dwordx4 v[128:129], off
	s_waitcnt vmcnt(8)
	s_waitcnt lgkmcnt(0)
	s_barrier
	s_setprio 1
	s_waitcnt lgkmcnt(0)
	v_mfma_f32_16x16x32_bf16 v[104:107], v[136:139], v[198:201], v[104:107]
	v_mfma_f32_16x16x32_bf16 v[132:135], v[140:143], v[202:205], v[104:107]
	v_mfma_f32_16x16x32_bf16 v[104:107], v[144:147], v[198:201], v[124:127]
	v_mfma_f32_16x16x32_bf16 v[128:131], v[148:151], v[202:205], v[104:107]
	v_mfma_f32_16x16x32_bf16 v[104:107], v[136:139], v[206:209], v[112:115]
	v_mfma_f32_16x16x32_bf16 v[112:115], v[140:143], v[210:213], v[104:107]
	v_mfma_f32_16x16x32_bf16 v[104:107], v[144:147], v[206:209], v[108:111]
	v_mfma_f32_16x16x32_bf16 v[92:95], v[136:139], v[214:217], v[92:95]
	v_mfma_f32_16x16x32_bf16 v[88:91], v[144:147], v[214:217], v[88:91]
	v_mfma_f32_16x16x32_bf16 v[76:79], v[136:139], v[226:229], v[76:79]
	v_mfma_f32_16x16x32_bf16 v[72:75], v[144:147], v[226:229], v[72:75]
	v_mfma_f32_16x16x32_bf16 v[108:111], v[148:151], v[210:213], v[104:107]
	v_mfma_f32_16x16x32_bf16 v[92:95], v[140:143], v[218:221], v[92:95]
	v_mfma_f32_16x16x32_bf16 v[88:91], v[148:151], v[218:221], v[88:91]
	v_mfma_f32_16x16x32_bf16 v[76:79], v[140:143], v[230:233], v[76:79]
	v_mfma_f32_16x16x32_bf16 v[72:75], v[148:151], v[230:233], v[72:75]
	s_setprio 0
	s_setprio 1
	v_mfma_f32_16x16x32_bf16 v[104:107], v[152:155], v[198:201], v[120:123]
	v_mfma_f32_16x16x32_bf16 v[120:123], v[156:159], v[202:205], v[104:107]
	v_mfma_f32_16x16x32_bf16 v[104:107], v[160:163], v[198:201], v[116:119]
	v_mfma_f32_16x16x32_bf16 v[100:103], v[152:155], v[206:209], v[100:103]
	v_mfma_f32_16x16x32_bf16 v[96:99], v[160:163], v[206:209], v[96:99]
	v_mfma_f32_16x16x32_bf16 v[84:87], v[152:155], v[214:217], v[84:87]
	v_mfma_f32_16x16x32_bf16 v[80:83], v[160:163], v[214:217], v[80:83]
	v_mfma_f32_16x16x32_bf16 v[68:71], v[152:155], v[226:229], v[68:71]
	v_mfma_f32_16x16x32_bf16 v[64:67], v[160:163], v[226:229], v[64:67]
	v_mfma_f32_16x16x32_bf16 v[116:119], v[164:167], v[202:205], v[104:107]
	v_mfma_f32_16x16x32_bf16 v[100:103], v[156:159], v[210:213], v[100:103]
	v_mfma_f32_16x16x32_bf16 v[96:99], v[164:167], v[210:213], v[96:99]
	v_mfma_f32_16x16x32_bf16 v[84:87], v[156:159], v[218:221], v[84:87]
	v_mfma_f32_16x16x32_bf16 v[80:83], v[164:167], v[218:221], v[80:83]
	v_mfma_f32_16x16x32_bf16 v[68:71], v[156:159], v[230:233], v[68:71]
	v_mfma_f32_16x16x32_bf16 v[64:67], v[164:167], v[230:233], v[64:67]
	s_setprio 0
	s_barrier
	s_add_i32 s40, s80, s3
	v_lshl_add_u64 v[180:181], v[180:181], 0, s[18:19]
	s_mov_b32 m0, s40
	ds_read_b128 v[104:107], v195 offset:49152
	ds_read_b128 v[124:127], v195 offset:50176
	ds_read_b128 v[198:201], v195 offset:51200
	ds_read_b128 v[202:205], v195 offset:52224
	ds_read_b128 v[206:209], v195 offset:53248
	ds_read_b128 v[210:213], v195 offset:54272
	ds_read_b128 v[214:217], v195 offset:55296
	ds_read_b128 v[218:221], v195 offset:56320
	global_load_lds_dwordx4 v[180:181], off
	s_add_i32 m0, s40, 0x2000
	s_add_u32 s38, s38, 0x80080
	v_lshl_add_u64 v[180:181], v[222:223], 0, s[18:19]
	s_addc_u32 s39, s39, 0
	s_add_i32 s40, s81, s3
	global_load_lds_dwordx4 v[180:181], off
	v_lshl_add_u64 v[180:181], s[38:39], 0, v[186:187]
	s_mov_b32 m0, s40
	s_nop 0
	global_load_lds_dwordx4 v[180:181], off
	v_lshl_add_u64 v[180:181], s[38:39], 0, v[184:185]
	s_add_i32 m0, s40, 0x2000
	s_nop 0
	global_load_lds_dwordx4 v[180:181], off
	v_lshl_add_u64 v[180:181], v[234:235], 0, s[18:19]
	s_mov_b32 m0, s70
	s_nop 0
	global_load_lds_dwordx4 v[180:181], off
	v_lshl_add_u64 v[180:181], v[236:237], 0, s[18:19]
	s_mov_b32 m0, s71
	s_nop 0
	global_load_lds_dwordx4 v[180:181], off
	s_waitcnt vmcnt(8)
	s_waitcnt lgkmcnt(0)
	s_barrier
	s_setprio 1
	s_waitcnt lgkmcnt(0)
	v_mfma_f32_16x16x32_bf16 v[60:63], v[136:139], v[104:107], v[60:63]
	v_mfma_f32_16x16x32_bf16 v[56:59], v[144:147], v[104:107], v[56:59]
	v_mfma_f32_16x16x32_bf16 v[44:47], v[136:139], v[198:201], v[44:47]
	v_mfma_f32_16x16x32_bf16 v[40:43], v[144:147], v[198:201], v[40:43]
	v_mfma_f32_16x16x32_bf16 v[28:31], v[136:139], v[206:209], v[28:31]
	v_mfma_f32_16x16x32_bf16 v[24:27], v[144:147], v[206:209], v[24:27]
	v_mfma_f32_16x16x32_bf16 v[12:15], v[136:139], v[214:217], v[12:15]
	v_mfma_f32_16x16x32_bf16 v[8:11], v[144:147], v[214:217], v[8:11]
	v_mfma_f32_16x16x32_bf16 v[60:63], v[140:143], v[124:127], v[60:63]
	v_mfma_f32_16x16x32_bf16 v[56:59], v[148:151], v[124:127], v[56:59]
	v_mfma_f32_16x16x32_bf16 v[44:47], v[140:143], v[202:205], v[44:47]
	v_mfma_f32_16x16x32_bf16 v[40:43], v[148:151], v[202:205], v[40:43]
	v_mfma_f32_16x16x32_bf16 v[28:31], v[140:143], v[210:213], v[28:31]
	v_mfma_f32_16x16x32_bf16 v[24:27], v[148:151], v[210:213], v[24:27]
	v_mfma_f32_16x16x32_bf16 v[12:15], v[140:143], v[218:221], v[12:15]
	v_mfma_f32_16x16x32_bf16 v[8:11], v[148:151], v[218:221], v[8:11]
	s_setprio 0
	s_setprio 1
	v_mfma_f32_16x16x32_bf16 v[52:55], v[152:155], v[104:107], v[52:55]
	s_add_i32 s79, s79, 2
	v_mfma_f32_16x16x32_bf16 v[48:51], v[160:163], v[104:107], v[48:51]
	s_add_u32 s36, s36, 0x100
	v_mfma_f32_16x16x32_bf16 v[36:39], v[152:155], v[198:201], v[36:39]
	s_addc_u32 s37, s37, 0
	v_mfma_f32_16x16x32_bf16 v[32:35], v[160:163], v[198:201], v[32:35]
	s_cmp_gt_u32 s79, 29
	v_mfma_f32_16x16x32_bf16 v[20:23], v[152:155], v[206:209], v[20:23]
	v_mfma_f32_16x16x32_bf16 v[16:19], v[160:163], v[206:209], v[16:19]
	v_mfma_f32_16x16x32_bf16 v[4:7], v[152:155], v[214:217], v[4:7]
	v_mfma_f32_16x16x32_bf16 v[0:3], v[160:163], v[214:217], v[0:3]
	v_mfma_f32_16x16x32_bf16 v[52:55], v[156:159], v[124:127], v[52:55]
	v_mfma_f32_16x16x32_bf16 v[48:51], v[164:167], v[124:127], v[48:51]
	v_mfma_f32_16x16x32_bf16 v[36:39], v[156:159], v[202:205], v[36:39]
	v_mfma_f32_16x16x32_bf16 v[32:35], v[164:167], v[202:205], v[32:35]
	v_mfma_f32_16x16x32_bf16 v[20:23], v[156:159], v[210:213], v[20:23]
	v_mfma_f32_16x16x32_bf16 v[16:19], v[164:167], v[210:213], v[16:19]
	v_mfma_f32_16x16x32_bf16 v[4:7], v[156:159], v[218:221], v[4:7]
	v_mfma_f32_16x16x32_bf16 v[0:3], v[164:167], v[218:221], v[0:3]
	s_setprio 0
	s_barrier
	s_cbranch_scc1 .LBB0_952
	v_mov_b32_e32 v180, v179
	v_mov_b32_e32 v168, v183
	v_mov_b32_e32 v182, v196
	v_mov_b32_e32 v178, v197
	s_branch .LBB0_948

.LBB0_1067:
	ds_read_b128 v[16:19], v188
	ds_read_b128 v[20:23], v188 offset:1024
	ds_read_b128 v[24:27], v188 offset:2048
	ds_read_b128 v[28:31], v188 offset:3072
	ds_read_b128 v[0:3], v189
	ds_read_b128 v[4:7], v189 offset:1024
	ds_read_b128 v[8:11], v189 offset:2048
	ds_read_b128 v[12:15], v189 offset:3072
	s_add_u32 s30, s28, 0xfffc0080
	s_addc_u32 s31, s29, -1
	s_cmp_eq_u32 s74, 12
	s_cselect_b32 s35, s23, s31
	s_cselect_b32 s34, s70, s30
	s_cselect_b32 s31, s21, s73
	s_cselect_b32 s30, s71, s72
	v_lshl_add_u64 v[218:219], s[28:29], 0, v[168:169]
	s_add_i32 m0, s40, 0xc000
	ds_read_b128 v[176:179], v190
	ds_read_b128 v[180:183], v190 offset:1024
	ds_read_b128 v[194:197], v190 offset:2048
	ds_read_b128 v[198:201], v190 offset:3072
	ds_read_b128 v[202:205], v190 offset:4096
	ds_read_b128 v[206:209], v190 offset:5120
	ds_read_b128 v[210:213], v190 offset:6144
	ds_read_b128 v[214:217], v190 offset:7168
	global_load_lds_dwordx4 v[218:219], off
	v_lshl_add_u64 v[218:219], s[28:29], 0, v[170:171]
	s_add_i32 m0, s40, 0xe000
	s_nop 0
	global_load_lds_dwordx4 v[218:219], off
	s_waitcnt vmcnt(8)
	s_waitcnt lgkmcnt(0)
	s_barrier
	s_setprio 1
	s_waitcnt lgkmcnt(0)
	v_mfma_scale_f32_16x16x128_f8f6f4 v[156:159], v[16:23], v[176:183], v[156:159], v184, v184 op_sel_hi:[0,0,0]
	v_mfma_scale_f32_16x16x128_f8f6f4 v[152:155], v[24:31], v[176:183], v[152:155], v184, v184 op_sel_hi:[0,0,0]
	v_mfma_scale_f32_16x16x128_f8f6f4 v[140:143], v[16:23], v[194:201], v[140:143], v184, v184 op_sel_hi:[0,0,0]
	v_mfma_scale_f32_16x16x128_f8f6f4 v[136:139], v[24:31], v[194:201], v[136:139], v184, v184 op_sel_hi:[0,0,0]
	v_mfma_scale_f32_16x16x128_f8f6f4 v[124:127], v[16:23], v[202:209], v[124:127], v184, v184 op_sel_hi:[0,0,0]
	v_mfma_scale_f32_16x16x128_f8f6f4 v[120:123], v[24:31], v[202:209], v[120:123], v184, v184 op_sel_hi:[0,0,0]
	v_mfma_scale_f32_16x16x128_f8f6f4 v[108:111], v[16:23], v[210:217], v[108:111], v184, v184 op_sel_hi:[0,0,0]
	v_mfma_scale_f32_16x16x128_f8f6f4 v[104:107], v[24:31], v[210:217], v[104:107], v184, v184 op_sel_hi:[0,0,0]
	s_setprio 0
	s_setprio 1
	v_mfma_scale_f32_16x16x128_f8f6f4 v[148:151], v[0:7], v[176:183], v[148:151], v184, v184 op_sel_hi:[0,0,0]
	v_mfma_scale_f32_16x16x128_f8f6f4 v[144:147], v[8:15], v[176:183], v[144:147], v184, v184 op_sel_hi:[0,0,0]
	v_mfma_scale_f32_16x16x128_f8f6f4 v[132:135], v[0:7], v[194:201], v[132:135], v184, v184 op_sel_hi:[0,0,0]
	v_mfma_scale_f32_16x16x128_f8f6f4 v[128:131], v[8:15], v[194:201], v[128:131], v184, v184 op_sel_hi:[0,0,0]
	v_mfma_scale_f32_16x16x128_f8f6f4 v[116:119], v[0:7], v[202:209], v[116:119], v184, v184 op_sel_hi:[0,0,0]
	v_mfma_scale_f32_16x16x128_f8f6f4 v[112:115], v[8:15], v[202:209], v[112:115], v184, v184 op_sel_hi:[0,0,0]
	v_mfma_scale_f32_16x16x128_f8f6f4 v[100:103], v[0:7], v[210:217], v[100:103], v184, v184 op_sel_hi:[0,0,0]
	v_mfma_scale_f32_16x16x128_f8f6f4 v[96:99], v[8:15], v[210:217], v[96:99], v184, v184 op_sel_hi:[0,0,0]
	s_setprio 0
	s_barrier
	s_add_i32 s75, s65, s3
	v_lshl_add_u64 v[176:177], s[30:31], 0, v[164:165]
	s_mov_b32 m0, s75
	ds_read_b128 v[194:197], v190 offset:16384
	ds_read_b128 v[198:201], v190 offset:17408
	ds_read_b128 v[202:205], v190 offset:18432
	ds_read_b128 v[206:209], v190 offset:19456
	ds_read_b128 v[210:213], v190 offset:20480
	ds_read_b128 v[214:217], v190 offset:21504
	ds_read_b128 v[226:229], v190 offset:22528
	ds_read_b128 v[230:233], v190 offset:23552
	global_load_lds_dwordx4 v[176:177], off
	s_add_i32 m0, s75, 0x2000
	s_add_u32 s76, s30, 0x40000
	v_lshl_add_u64 v[178:179], s[30:31], 0, v[160:161]
	s_addc_u32 s77, s31, 0
	s_add_i32 s75, s66, s3
	global_load_lds_dwordx4 v[178:179], off
	v_lshl_add_u64 v[180:181], s[76:77], 0, v[164:165]
	s_mov_b32 m0, s75
	v_lshl_add_u64 v[182:183], s[34:35], 0, v[162:163]
	global_load_lds_dwordx4 v[180:181], off
	v_lshl_add_u64 v[180:181], s[76:77], 0, v[160:161]
	s_add_i32 m0, s75, 0x2000
	s_nop 0
	global_load_lds_dwordx4 v[180:181], off
	v_lshl_add_u64 v[180:181], s[34:35], 0, v[166:167]
	s_mov_b32 m0, s40
	s_nop 0
	global_load_lds_dwordx4 v[180:181], off
	s_mov_b32 m0, s41
	s_nop 0
	global_load_lds_dwordx4 v[182:183], off
	s_waitcnt vmcnt(8)
	s_waitcnt lgkmcnt(0)
	s_barrier
	s_setprio 1
	s_waitcnt lgkmcnt(0)
	v_mfma_scale_f32_16x16x128_f8f6f4 v[92:95], v[16:23], v[194:201], v[92:95], v184, v184 op_sel_hi:[0,0,0]
	v_mfma_scale_f32_16x16x128_f8f6f4 v[88:91], v[24:31], v[194:201], v[88:91], v184, v184 op_sel_hi:[0,0,0]
	v_mfma_scale_f32_16x16x128_f8f6f4 v[76:79], v[16:23], v[202:209], v[76:79], v184, v184 op_sel_hi:[0,0,0]
	v_mfma_scale_f32_16x16x128_f8f6f4 v[72:75], v[24:31], v[202:209], v[72:75], v184, v184 op_sel_hi:[0,0,0]
	v_mfma_scale_f32_16x16x128_f8f6f4 v[60:63], v[16:23], v[210:217], v[60:63], v184, v184 op_sel_hi:[0,0,0]
	v_mfma_scale_f32_16x16x128_f8f6f4 v[56:59], v[24:31], v[210:217], v[56:59], v184, v184 op_sel_hi:[0,0,0]
	v_mfma_scale_f32_16x16x128_f8f6f4 v[44:47], v[16:23], v[226:233], v[44:47], v184, v184 op_sel_hi:[0,0,0]
	v_mfma_scale_f32_16x16x128_f8f6f4 v[40:43], v[24:31], v[226:233], v[40:43], v184, v184 op_sel_hi:[0,0,0]
	s_setprio 0
	s_setprio 1
	v_mfma_scale_f32_16x16x128_f8f6f4 v[84:87], v[0:7], v[194:201], v[84:87], v184, v184 op_sel_hi:[0,0,0]
	v_mfma_scale_f32_16x16x128_f8f6f4 v[80:83], v[8:15], v[194:201], v[80:83], v184, v184 op_sel_hi:[0,0,0]
	v_mfma_scale_f32_16x16x128_f8f6f4 v[68:71], v[0:7], v[202:209], v[68:71], v184, v184 op_sel_hi:[0,0,0]
	v_mfma_scale_f32_16x16x128_f8f6f4 v[64:67], v[8:15], v[202:209], v[64:67], v184, v184 op_sel_hi:[0,0,0]
	v_mfma_scale_f32_16x16x128_f8f6f4 v[52:55], v[0:7], v[210:217], v[52:55], v184, v184 op_sel_hi:[0,0,0]
	v_mfma_scale_f32_16x16x128_f8f6f4 v[48:51], v[8:15], v[210:217], v[48:51], v184, v184 op_sel_hi:[0,0,0]
	v_mfma_scale_f32_16x16x128_f8f6f4 v[36:39], v[0:7], v[226:233], v[36:39], v184, v184 op_sel_hi:[0,0,0]
	v_mfma_scale_f32_16x16x128_f8f6f4 v[32:35], v[8:15], v[226:233], v[32:35], v184, v184 op_sel_hi:[0,0,0]
	s_setprio 0
	s_barrier
	s_add_i32 s75, 0, 0x18000
	s_add_i32 s76, 0, 0x1c000
	v_add_u32_e32 v12, s75, v186
	v_add_u32_e32 v28, s76, v186
	ds_read_b128 v[0:3], v12
	ds_read_b128 v[4:7], v12 offset:1024
	ds_read_b128 v[8:11], v12 offset:2048
	ds_read_b128 v[12:15], v12 offset:3072
	ds_read_b128 v[16:19], v28
	ds_read_b128 v[20:23], v28 offset:1024
	ds_read_b128 v[24:27], v28 offset:2048
	ds_read_b128 v[28:31], v28 offset:3072
	s_add_u32 s34, s34, 0x40000
	s_addc_u32 s35, s35, 0
	s_mov_b32 m0, s44
	v_lshl_add_u64 v[218:219], s[34:35], 0, v[166:167]
	ds_read_b128 v[194:197], v190 offset:32768
	ds_read_b128 v[198:201], v190 offset:33792
	ds_read_b128 v[202:205], v190 offset:34816
	ds_read_b128 v[206:209], v190 offset:35840
	ds_read_b128 v[210:213], v190 offset:36864
	ds_read_b128 v[214:217], v190 offset:37888
	ds_read_b128 v[226:229], v190 offset:38912
	ds_read_b128 v[230:233], v190 offset:39936
	global_load_lds_dwordx4 v[218:219], off
	v_lshl_add_u64 v[218:219], s[34:35], 0, v[162:163]
	s_mov_b32 m0, s45
	s_nop 0
	global_load_lds_dwordx4 v[218:219], off
	s_waitcnt vmcnt(8)
	s_waitcnt lgkmcnt(0)
	s_barrier
	s_setprio 1
	s_waitcnt lgkmcnt(0)
	v_mfma_scale_f32_16x16x128_f8f6f4 v[156:159], v[0:7], v[194:201], v[156:159], v184, v184 op_sel_hi:[0,0,0]
	v_mfma_scale_f32_16x16x128_f8f6f4 v[152:155], v[8:15], v[194:201], v[152:155], v184, v184 op_sel_hi:[0,0,0]
	v_mfma_scale_f32_16x16x128_f8f6f4 v[140:143], v[0:7], v[202:209], v[140:143], v184, v184 op_sel_hi:[0,0,0]
	v_mfma_scale_f32_16x16x128_f8f6f4 v[136:139], v[8:15], v[202:209], v[136:139], v184, v184 op_sel_hi:[0,0,0]
	v_mfma_scale_f32_16x16x128_f8f6f4 v[124:127], v[0:7], v[210:217], v[124:127], v184, v184 op_sel_hi:[0,0,0]
	v_mfma_scale_f32_16x16x128_f8f6f4 v[120:123], v[8:15], v[210:217], v[120:123], v184, v184 op_sel_hi:[0,0,0]
	v_mfma_scale_f32_16x16x128_f8f6f4 v[108:111], v[0:7], v[226:233], v[108:111], v184, v184 op_sel_hi:[0,0,0]
	v_mfma_scale_f32_16x16x128_f8f6f4 v[104:107], v[8:15], v[226:233], v[104:107], v184, v184 op_sel_hi:[0,0,0]
	s_setprio 0
	s_setprio 1
	v_mfma_scale_f32_16x16x128_f8f6f4 v[148:151], v[16:23], v[194:201], v[148:151], v184, v184 op_sel_hi:[0,0,0]
	v_mfma_scale_f32_16x16x128_f8f6f4 v[144:147], v[24:31], v[194:201], v[144:147], v184, v184 op_sel_hi:[0,0,0]
	v_mfma_scale_f32_16x16x128_f8f6f4 v[132:135], v[16:23], v[202:209], v[132:135], v184, v184 op_sel_hi:[0,0,0]
	v_mfma_scale_f32_16x16x128_f8f6f4 v[128:131], v[24:31], v[202:209], v[128:131], v184, v184 op_sel_hi:[0,0,0]
	v_mfma_scale_f32_16x16x128_f8f6f4 v[116:119], v[16:23], v[210:217], v[116:119], v184, v184 op_sel_hi:[0,0,0]
	v_mfma_scale_f32_16x16x128_f8f6f4 v[112:115], v[24:31], v[210:217], v[112:115], v184, v184 op_sel_hi:[0,0,0]
	v_mfma_scale_f32_16x16x128_f8f6f4 v[100:103], v[16:23], v[226:233], v[100:103], v184, v184 op_sel_hi:[0,0,0]
	v_mfma_scale_f32_16x16x128_f8f6f4 v[96:99], v[24:31], v[226:233], v[96:99], v184, v184 op_sel_hi:[0,0,0]
	s_setprio 0
	s_barrier
	s_add_i32 s34, s75, s3
	v_lshl_add_u64 v[176:177], v[176:177], 0, s[16:17]
	s_mov_b32 m0, s34
	ds_read_b128 v[194:197], v190 offset:49152
	ds_read_b128 v[198:201], v190 offset:50176
	ds_read_b128 v[202:205], v190 offset:51200
	ds_read_b128 v[206:209], v190 offset:52224
	ds_read_b128 v[210:213], v190 offset:53248
	ds_read_b128 v[214:217], v190 offset:54272
	ds_read_b128 v[226:229], v190 offset:55296
	ds_read_b128 v[230:233], v190 offset:56320
	global_load_lds_dwordx4 v[176:177], off
	s_add_i32 m0, s34, 0x2000
	s_add_u32 s30, s30, 0x40080
	v_lshl_add_u64 v[176:177], v[178:179], 0, s[16:17]
	s_addc_u32 s31, s31, 0
	s_add_i32 s34, s76, s3
	global_load_lds_dwordx4 v[176:177], off
	v_lshl_add_u64 v[176:177], s[30:31], 0, v[164:165]
	s_mov_b32 m0, s34
	s_nop 0
	global_load_lds_dwordx4 v[176:177], off
	v_lshl_add_u64 v[176:177], s[30:31], 0, v[160:161]
	s_add_i32 m0, s34, 0x2000
	s_nop 0
	global_load_lds_dwordx4 v[176:177], off
	v_lshl_add_u64 v[176:177], v[180:181], 0, s[16:17]
	s_mov_b32 m0, s61
	s_nop 0
	global_load_lds_dwordx4 v[176:177], off
	v_lshl_add_u64 v[176:177], v[182:183], 0, s[16:17]
	s_mov_b32 m0, s62
	s_nop 0
	global_load_lds_dwordx4 v[176:177], off
	s_waitcnt vmcnt(8)
	s_waitcnt lgkmcnt(0)
	s_barrier
	s_setprio 1
	s_waitcnt lgkmcnt(0)
	v_mfma_scale_f32_16x16x128_f8f6f4 v[92:95], v[0:7], v[194:201], v[92:95], v184, v184 op_sel_hi:[0,0,0]
	s_add_i32 s74, s74, 2
	v_mfma_scale_f32_16x16x128_f8f6f4 v[88:91], v[8:15], v[194:201], v[88:91], v184, v184 op_sel_hi:[0,0,0]
	s_add_u32 s28, s28, 0x100
	v_mfma_scale_f32_16x16x128_f8f6f4 v[76:79], v[0:7], v[202:209], v[76:79], v184, v184 op_sel_hi:[0,0,0]
	s_addc_u32 s29, s29, 0
	v_mfma_scale_f32_16x16x128_f8f6f4 v[72:75], v[8:15], v[202:209], v[72:75], v184, v184 op_sel_hi:[0,0,0]
	s_add_u32 s72, s72, 0x100
	v_mfma_scale_f32_16x16x128_f8f6f4 v[60:63], v[0:7], v[210:217], v[60:63], v184, v184 op_sel_hi:[0,0,0]
	s_addc_u32 s73, s73, 0
	v_mfma_scale_f32_16x16x128_f8f6f4 v[56:59], v[8:15], v[210:217], v[56:59], v184, v184 op_sel_hi:[0,0,0]
	s_cmp_gt_u32 s74, 13
	v_mfma_scale_f32_16x16x128_f8f6f4 v[44:47], v[0:7], v[226:233], v[44:47], v184, v184 op_sel_hi:[0,0,0]
	v_mfma_scale_f32_16x16x128_f8f6f4 v[40:43], v[8:15], v[226:233], v[40:43], v184, v184 op_sel_hi:[0,0,0]
	s_setprio 0
	s_setprio 1
	v_mfma_scale_f32_16x16x128_f8f6f4 v[84:87], v[16:23], v[194:201], v[84:87], v184, v184 op_sel_hi:[0,0,0]
	v_mfma_scale_f32_16x16x128_f8f6f4 v[80:83], v[24:31], v[194:201], v[80:83], v184, v184 op_sel_hi:[0,0,0]
	v_mfma_scale_f32_16x16x128_f8f6f4 v[68:71], v[16:23], v[202:209], v[68:71], v184, v184 op_sel_hi:[0,0,0]
	v_mfma_scale_f32_16x16x128_f8f6f4 v[64:67], v[24:31], v[202:209], v[64:67], v184, v184 op_sel_hi:[0,0,0]
	v_mfma_scale_f32_16x16x128_f8f6f4 v[52:55], v[16:23], v[210:217], v[52:55], v184, v184 op_sel_hi:[0,0,0]
	v_mfma_scale_f32_16x16x128_f8f6f4 v[48:51], v[24:31], v[210:217], v[48:51], v184, v184 op_sel_hi:[0,0,0]
	v_mfma_scale_f32_16x16x128_f8f6f4 v[36:39], v[16:23], v[226:233], v[36:39], v184, v184 op_sel_hi:[0,0,0]
	v_mfma_scale_f32_16x16x128_f8f6f4 v[32:35], v[24:31], v[226:233], v[32:35], v184, v184 op_sel_hi:[0,0,0]
	s_setprio 0
	s_barrier
	s_cbranch_scc0 .LBB0_1067
	s_and_b64 vcc, exec, s[18:19]
	s_cbranch_vccz .LBB0_1070
	s_barrier

.LBB0_1259:
	s_add_u32 s26, s20, s28
	s_addc_u32 s27, s21, s29
	s_add_u32 s78, s26, 0x100
	s_addc_u32 s79, s27, 0
	s_and_b64 s[26:27], s[34:35], exec
	s_cselect_b32 s27, s79, s75
	s_cselect_b32 s26, s78, s76
	s_add_u32 s78, s71, s28
	s_addc_u32 s79, s72, s29
	s_and_b64 s[34:35], s[34:35], exec
	s_cselect_b32 s35, s79, s73
	s_cselect_b32 s34, s78, s74
	s_mov_b32 m0, s41
	v_lshl_add_u64 v[172:173], s[34:35], 0, v[178:179]
	v_lshl_add_u64 v[170:171], s[34:35], 0, v[176:177]
	s_add_u32 s34, s34, s30
	ds_read_b128 v[198:201], v193 offset:16384
	ds_read_b128 v[202:205], v193 offset:17408
	ds_read_b128 v[206:209], v193 offset:18432
	ds_read_b128 v[210:213], v193 offset:19456
	ds_read_b128 v[214:217], v193 offset:20480
	ds_read_b128 v[218:221], v193 offset:21504
	ds_read_b128 v[226:229], v193 offset:22528
	ds_read_b128 v[230:233], v193 offset:23552
	global_load_lds_dwordx4 v[172:173], off
	s_mov_b32 m0, s44
	s_addc_u32 s35, s35, s31
	global_load_lds_dwordx4 v[170:171], off
	v_lshl_add_u64 v[180:181], s[34:35], 0, v[178:179]
	s_mov_b32 m0, s45
	v_lshl_add_u64 v[178:179], s[34:35], 0, v[176:177]
	global_load_lds_dwordx4 v[180:181], off
	s_mov_b32 m0, s60
	v_lshl_add_u64 v[174:175], s[26:27], 0, v[184:185]
	global_load_lds_dwordx4 v[178:179], off
	s_mov_b32 m0, s40
	v_lshl_add_u64 v[176:177], s[26:27], 0, v[182:183]
	global_load_lds_dwordx4 v[174:175], off
	s_mov_b32 m0, s61
	s_nop 0
	global_load_lds_dwordx4 v[176:177], off
	s_waitcnt vmcnt(8)
	s_waitcnt lgkmcnt(0)
	s_barrier
	s_setprio 1
	s_waitcnt lgkmcnt(0)
	v_mfma_scale_f32_16x16x128_f8f6f4 v[92:95], v[16:23], v[198:205], v[92:95], v190, v190 op_sel_hi:[0,0,0]
	v_mfma_scale_f32_16x16x128_f8f6f4 v[88:91], v[24:31], v[198:205], v[88:91], v190, v190 op_sel_hi:[0,0,0]
	v_mfma_scale_f32_16x16x128_f8f6f4 v[76:79], v[16:23], v[206:213], v[76:79], v190, v190 op_sel_hi:[0,0,0]
	v_mfma_scale_f32_16x16x128_f8f6f4 v[72:75], v[24:31], v[206:213], v[72:75], v190, v190 op_sel_hi:[0,0,0]
	v_mfma_scale_f32_16x16x128_f8f6f4 v[60:63], v[16:23], v[214:221], v[60:63], v190, v190 op_sel_hi:[0,0,0]
	v_mfma_scale_f32_16x16x128_f8f6f4 v[56:59], v[24:31], v[214:221], v[56:59], v190, v190 op_sel_hi:[0,0,0]
	v_mfma_scale_f32_16x16x128_f8f6f4 v[44:47], v[16:23], v[226:233], v[44:47], v190, v190 op_sel_hi:[0,0,0]
	v_mfma_scale_f32_16x16x128_f8f6f4 v[40:43], v[24:31], v[226:233], v[40:43], v190, v190 op_sel_hi:[0,0,0]
	s_setprio 0
	s_setprio 1
	v_mfma_scale_f32_16x16x128_f8f6f4 v[84:87], v[0:7], v[198:205], v[84:87], v190, v190 op_sel_hi:[0,0,0]
	v_mfma_scale_f32_16x16x128_f8f6f4 v[80:83], v[8:15], v[198:205], v[80:83], v190, v190 op_sel_hi:[0,0,0]
	v_mfma_scale_f32_16x16x128_f8f6f4 v[68:71], v[0:7], v[206:213], v[68:71], v190, v190 op_sel_hi:[0,0,0]
	v_mfma_scale_f32_16x16x128_f8f6f4 v[64:67], v[8:15], v[206:213], v[64:67], v190, v190 op_sel_hi:[0,0,0]
	v_mfma_scale_f32_16x16x128_f8f6f4 v[52:55], v[0:7], v[214:221], v[52:55], v190, v190 op_sel_hi:[0,0,0]
	v_mfma_scale_f32_16x16x128_f8f6f4 v[48:51], v[8:15], v[214:221], v[48:51], v190, v190 op_sel_hi:[0,0,0]
	v_mfma_scale_f32_16x16x128_f8f6f4 v[36:39], v[0:7], v[226:233], v[36:39], v190, v190 op_sel_hi:[0,0,0]
	v_mfma_scale_f32_16x16x128_f8f6f4 v[32:35], v[8:15], v[226:233], v[32:35], v190, v190 op_sel_hi:[0,0,0]
	s_setprio 0
	s_barrier
	s_add_i32 s34, 0, 0x18000
	s_add_i32 s35, 0, 0x1c000
	v_add_u32_e32 v12, s34, v192
	v_add_u32_e32 v28, s35, v192
	ds_read_b128 v[0:3], v12
	ds_read_b128 v[4:7], v12 offset:1024
	ds_read_b128 v[8:11], v12 offset:2048
	ds_read_b128 v[12:15], v12 offset:3072
	ds_read_b128 v[16:19], v28
	ds_read_b128 v[20:23], v28 offset:1024
	ds_read_b128 v[24:27], v28 offset:2048
	ds_read_b128 v[28:31], v28 offset:3072
	s_add_u32 s26, s26, s30
	s_addc_u32 s27, s27, s31
	s_mov_b32 m0, s62
	v_lshl_add_u64 v[184:185], s[26:27], 0, v[184:185]
	ds_read_b128 v[198:201], v193 offset:32768
	ds_read_b128 v[202:205], v193 offset:33792
	ds_read_b128 v[206:209], v193 offset:34816
	ds_read_b128 v[210:213], v193 offset:35840
	ds_read_b128 v[214:217], v193 offset:36864
	ds_read_b128 v[218:221], v193 offset:37888
	ds_read_b128 v[226:229], v193 offset:38912
	ds_read_b128 v[230:233], v193 offset:39936
	global_load_lds_dwordx4 v[184:185], off
	v_lshl_add_u64 v[182:183], s[26:27], 0, v[182:183]
	s_mov_b32 m0, s63
	s_nop 0
	global_load_lds_dwordx4 v[182:183], off
	s_waitcnt vmcnt(8)
	s_waitcnt lgkmcnt(0)
	s_barrier
	s_setprio 1
	s_waitcnt lgkmcnt(0)
	v_mfma_scale_f32_16x16x128_f8f6f4 v[156:159], v[0:7], v[198:205], v[156:159], v190, v190 op_sel_hi:[0,0,0]
	v_mfma_scale_f32_16x16x128_f8f6f4 v[152:155], v[8:15], v[198:205], v[152:155], v190, v190 op_sel_hi:[0,0,0]
	v_mfma_scale_f32_16x16x128_f8f6f4 v[140:143], v[0:7], v[206:213], v[140:143], v190, v190 op_sel_hi:[0,0,0]
	v_mfma_scale_f32_16x16x128_f8f6f4 v[136:139], v[8:15], v[206:213], v[136:139], v190, v190 op_sel_hi:[0,0,0]
	v_mfma_scale_f32_16x16x128_f8f6f4 v[124:127], v[0:7], v[214:221], v[124:127], v190, v190 op_sel_hi:[0,0,0]
	v_mfma_scale_f32_16x16x128_f8f6f4 v[120:123], v[8:15], v[214:221], v[120:123], v190, v190 op_sel_hi:[0,0,0]
	v_mfma_scale_f32_16x16x128_f8f6f4 v[108:111], v[0:7], v[226:233], v[108:111], v190, v190 op_sel_hi:[0,0,0]
	v_mfma_scale_f32_16x16x128_f8f6f4 v[104:107], v[8:15], v[226:233], v[104:107], v190, v190 op_sel_hi:[0,0,0]
	s_setprio 0
	s_setprio 1
	v_mfma_scale_f32_16x16x128_f8f6f4 v[148:151], v[16:23], v[198:205], v[148:151], v190, v190 op_sel_hi:[0,0,0]
	v_mfma_scale_f32_16x16x128_f8f6f4 v[144:147], v[24:31], v[198:205], v[144:147], v190, v190 op_sel_hi:[0,0,0]
	v_mfma_scale_f32_16x16x128_f8f6f4 v[132:135], v[16:23], v[206:213], v[132:135], v190, v190 op_sel_hi:[0,0,0]
	v_mfma_scale_f32_16x16x128_f8f6f4 v[128:131], v[24:31], v[206:213], v[128:131], v190, v190 op_sel_hi:[0,0,0]
	v_mfma_scale_f32_16x16x128_f8f6f4 v[116:119], v[16:23], v[214:221], v[116:119], v190, v190 op_sel_hi:[0,0,0]
	v_mfma_scale_f32_16x16x128_f8f6f4 v[112:115], v[24:31], v[214:221], v[112:115], v190, v190 op_sel_hi:[0,0,0]
	v_mfma_scale_f32_16x16x128_f8f6f4 v[100:103], v[16:23], v[226:233], v[100:103], v190, v190 op_sel_hi:[0,0,0]
	v_mfma_scale_f32_16x16x128_f8f6f4 v[96:99], v[24:31], v[226:233], v[96:99], v190, v190 op_sel_hi:[0,0,0]
	s_setprio 0
	s_barrier
	s_add_i32 s26, s34, s3
	v_lshl_add_u64 v[172:173], v[172:173], 0, s[16:17]
	s_mov_b32 m0, s26
	ds_read_b128 v[198:201], v193 offset:49152
	ds_read_b128 v[202:205], v193 offset:50176
	ds_read_b128 v[206:209], v193 offset:51200
	ds_read_b128 v[210:213], v193 offset:52224
	ds_read_b128 v[214:217], v193 offset:53248
	ds_read_b128 v[218:221], v193 offset:54272
	ds_read_b128 v[226:229], v193 offset:55296
	ds_read_b128 v[230:233], v193 offset:56320
	global_load_lds_dwordx4 v[172:173], off
	v_lshl_add_u64 v[170:171], v[170:171], 0, s[16:17]
	s_add_i32 m0, s26, 0x2000
	s_add_i32 s26, s35, s3
	global_load_lds_dwordx4 v[170:171], off
	v_lshl_add_u64 v[170:171], v[180:181], 0, s[16:17]
	s_mov_b32 m0, s26
	s_nop 0
	global_load_lds_dwordx4 v[170:171], off
	v_lshl_add_u64 v[170:171], v[178:179], 0, s[16:17]
	s_add_i32 m0, s26, 0x2000
	s_nop 0
	global_load_lds_dwordx4 v[170:171], off
	v_lshl_add_u64 v[170:171], v[174:175], 0, s[16:17]
	s_mov_b32 m0, s65
	s_nop 0
	global_load_lds_dwordx4 v[170:171], off
	v_lshl_add_u64 v[170:171], v[176:177], 0, s[16:17]
	s_mov_b32 m0, s66
	s_nop 0
	global_load_lds_dwordx4 v[170:171], off
	s_waitcnt vmcnt(8)
	s_waitcnt lgkmcnt(0)
	s_barrier
	s_setprio 1
	s_waitcnt lgkmcnt(0)
	v_mfma_scale_f32_16x16x128_f8f6f4 v[92:95], v[0:7], v[198:205], v[92:95], v190, v190 op_sel_hi:[0,0,0]
	s_add_i32 s77, s77, 2
	v_mfma_scale_f32_16x16x128_f8f6f4 v[88:91], v[8:15], v[198:205], v[88:91], v190, v190 op_sel_hi:[0,0,0]
	s_add_u32 s28, s28, 0x100
	v_mfma_scale_f32_16x16x128_f8f6f4 v[76:79], v[0:7], v[206:213], v[76:79], v190, v190 op_sel_hi:[0,0,0]
	s_addc_u32 s29, s29, 0
	v_mfma_scale_f32_16x16x128_f8f6f4 v[72:75], v[8:15], v[206:213], v[72:75], v190, v190 op_sel_hi:[0,0,0]
	s_cmp_gt_u32 s77, 41
	v_mfma_scale_f32_16x16x128_f8f6f4 v[60:63], v[0:7], v[214:221], v[60:63], v190, v190 op_sel_hi:[0,0,0]
	v_mfma_scale_f32_16x16x128_f8f6f4 v[56:59], v[8:15], v[214:221], v[56:59], v190, v190 op_sel_hi:[0,0,0]
	v_mfma_scale_f32_16x16x128_f8f6f4 v[44:47], v[0:7], v[226:233], v[44:47], v190, v190 op_sel_hi:[0,0,0]
	v_mfma_scale_f32_16x16x128_f8f6f4 v[40:43], v[8:15], v[226:233], v[40:43], v190, v190 op_sel_hi:[0,0,0]
	s_setprio 0
	s_setprio 1
	v_mfma_scale_f32_16x16x128_f8f6f4 v[84:87], v[16:23], v[198:205], v[84:87], v190, v190 op_sel_hi:[0,0,0]
	v_mfma_scale_f32_16x16x128_f8f6f4 v[80:83], v[24:31], v[198:205], v[80:83], v190, v190 op_sel_hi:[0,0,0]
	v_mfma_scale_f32_16x16x128_f8f6f4 v[68:71], v[16:23], v[206:213], v[68:71], v190, v190 op_sel_hi:[0,0,0]
	v_mfma_scale_f32_16x16x128_f8f6f4 v[64:67], v[24:31], v[206:213], v[64:67], v190, v190 op_sel_hi:[0,0,0]
	v_mfma_scale_f32_16x16x128_f8f6f4 v[52:55], v[16:23], v[214:221], v[52:55], v190, v190 op_sel_hi:[0,0,0]
	v_mfma_scale_f32_16x16x128_f8f6f4 v[48:51], v[24:31], v[214:221], v[48:51], v190, v190 op_sel_hi:[0,0,0]
	v_mfma_scale_f32_16x16x128_f8f6f4 v[36:39], v[16:23], v[226:233], v[36:39], v190, v190 op_sel_hi:[0,0,0]
	v_mfma_scale_f32_16x16x128_f8f6f4 v[32:35], v[24:31], v[226:233], v[32:35], v190, v190 op_sel_hi:[0,0,0]
	s_setprio 0
	s_barrier
	s_cbranch_scc1 .LBB0_1261
	v_mov_b32_e32 v172, v194
	v_mov_b32_e32 v160, v195
	v_mov_b32_e32 v174, v196
	v_mov_b32_e32 v170, v197
	s_mov_b64 s[26:27], s[30:31]
	s_branch .LBB0_1257

.LBB0_1356:
	ds_read_b128 v[144:147], v191
	ds_read_b128 v[148:151], v191 offset:1024
	ds_read_b128 v[152:155], v191 offset:2048
	ds_read_b128 v[156:159], v191 offset:3072
	ds_read_b128 v[160:163], v192
	ds_read_b128 v[164:167], v192 offset:1024
	ds_read_b128 v[168:171], v192 offset:2048
	ds_read_b128 v[172:175], v192 offset:3072
	s_add_u32 s36, s34, 0xfff80080
	s_addc_u32 s37, s35, -1
	s_cmp_eq_u32 s64, 28
	s_cselect_b32 s39, s9, s37
	s_cselect_b32 s38, s25, s36
	s_cselect_b32 s37, s23, s63
	s_cselect_b32 s36, s31, s62
	v_lshl_add_u64 v[216:217], s[34:35], 0, v[136:137]
	s_add_i32 m0, s42, 0xc000
	ds_read_b128 v[176:179], v193
	ds_read_b128 v[180:183], v193 offset:1024
	ds_read_b128 v[184:187], v193 offset:2048
	ds_read_b128 v[196:199], v193 offset:3072
	ds_read_b128 v[200:203], v193 offset:4096
	ds_read_b128 v[204:207], v193 offset:5120
	ds_read_b128 v[208:211], v193 offset:6144
	ds_read_b128 v[212:215], v193 offset:7168
	global_load_lds_dwordx4 v[216:217], off
	v_lshl_add_u64 v[216:217], s[34:35], 0, v[138:139]
	s_add_i32 m0, s42, 0xe000
	s_nop 0
	global_load_lds_dwordx4 v[216:217], off
	s_waitcnt vmcnt(8)
	s_waitcnt lgkmcnt(0)
	s_barrier
	s_setprio 1
	s_waitcnt lgkmcnt(0)
	v_mfma_f32_16x16x32_bf16 v[124:127], v[144:147], v[176:179], v[124:127]
	v_mfma_f32_16x16x32_bf16 v[120:123], v[152:155], v[176:179], v[120:123]
	v_mfma_f32_16x16x32_bf16 v[108:111], v[144:147], v[184:187], v[108:111]
	v_mfma_f32_16x16x32_bf16 v[104:107], v[152:155], v[184:187], v[104:107]
	v_mfma_f32_16x16x32_bf16 v[92:95], v[144:147], v[200:203], v[92:95]
	v_mfma_f32_16x16x32_bf16 v[88:91], v[152:155], v[200:203], v[88:91]
	v_mfma_f32_16x16x32_bf16 v[76:79], v[144:147], v[208:211], v[76:79]
	v_mfma_f32_16x16x32_bf16 v[72:75], v[152:155], v[208:211], v[72:75]
	v_mfma_f32_16x16x32_bf16 v[124:127], v[148:151], v[180:183], v[124:127]
	v_mfma_f32_16x16x32_bf16 v[120:123], v[156:159], v[180:183], v[120:123]
	v_mfma_f32_16x16x32_bf16 v[108:111], v[148:151], v[196:199], v[108:111]
	v_mfma_f32_16x16x32_bf16 v[104:107], v[156:159], v[196:199], v[104:107]
	v_mfma_f32_16x16x32_bf16 v[92:95], v[148:151], v[204:207], v[92:95]
	v_mfma_f32_16x16x32_bf16 v[88:91], v[156:159], v[204:207], v[88:91]
	v_mfma_f32_16x16x32_bf16 v[76:79], v[148:151], v[212:215], v[76:79]
	v_mfma_f32_16x16x32_bf16 v[72:75], v[156:159], v[212:215], v[72:75]
	s_setprio 0
	s_setprio 1
	v_mfma_f32_16x16x32_bf16 v[116:119], v[160:163], v[176:179], v[116:119]
	v_mfma_f32_16x16x32_bf16 v[112:115], v[168:171], v[176:179], v[112:115]
	v_mfma_f32_16x16x32_bf16 v[100:103], v[160:163], v[184:187], v[100:103]
	v_mfma_f32_16x16x32_bf16 v[96:99], v[168:171], v[184:187], v[96:99]
	v_mfma_f32_16x16x32_bf16 v[84:87], v[160:163], v[200:203], v[84:87]
	v_mfma_f32_16x16x32_bf16 v[80:83], v[168:171], v[200:203], v[80:83]
	v_mfma_f32_16x16x32_bf16 v[68:71], v[160:163], v[208:211], v[68:71]
	v_mfma_f32_16x16x32_bf16 v[64:67], v[168:171], v[208:211], v[64:67]
	v_mfma_f32_16x16x32_bf16 v[116:119], v[164:167], v[180:183], v[116:119]
	v_mfma_f32_16x16x32_bf16 v[112:115], v[172:175], v[180:183], v[112:115]
	v_mfma_f32_16x16x32_bf16 v[100:103], v[164:167], v[196:199], v[100:103]
	v_mfma_f32_16x16x32_bf16 v[96:99], v[172:175], v[196:199], v[96:99]
	v_mfma_f32_16x16x32_bf16 v[84:87], v[164:167], v[204:207], v[84:87]
	v_mfma_f32_16x16x32_bf16 v[80:83], v[172:175], v[204:207], v[80:83]
	v_mfma_f32_16x16x32_bf16 v[68:71], v[164:167], v[212:215], v[68:71]
	v_mfma_f32_16x16x32_bf16 v[64:67], v[172:175], v[212:215], v[64:67]
	s_setprio 0
	s_barrier
	s_add_i32 s65, s57, s3
	v_lshl_add_u64 v[216:217], s[36:37], 0, v[130:131]
	s_mov_b32 m0, s65
	ds_read_b128 v[176:179], v193 offset:16384
	ds_read_b128 v[180:183], v193 offset:17408
	ds_read_b128 v[184:187], v193 offset:18432
	ds_read_b128 v[196:199], v193 offset:19456
	ds_read_b128 v[200:203], v193 offset:20480
	ds_read_b128 v[204:207], v193 offset:21504
	ds_read_b128 v[208:211], v193 offset:22528
	ds_read_b128 v[212:215], v193 offset:23552
	global_load_lds_dwordx4 v[216:217], off
	s_add_i32 m0, s65, 0x2000
	s_add_u32 s66, s36, 0x80000
	v_lshl_add_u64 v[218:219], s[36:37], 0, v[134:135]
	s_addc_u32 s67, s37, 0
	s_add_i32 s65, s60, s3
	global_load_lds_dwordx4 v[218:219], off
	v_lshl_add_u64 v[220:221], s[66:67], 0, v[130:131]
	s_mov_b32 m0, s65
	v_lshl_add_u64 v[222:223], s[38:39], 0, v[132:133]
	global_load_lds_dwordx4 v[220:221], off
	v_lshl_add_u64 v[220:221], s[66:67], 0, v[134:135]
	s_add_i32 m0, s65, 0x2000
	s_nop 0
	global_load_lds_dwordx4 v[220:221], off
	v_lshl_add_u64 v[220:221], s[38:39], 0, v[128:129]
	s_mov_b32 m0, s42
	s_nop 0
	global_load_lds_dwordx4 v[220:221], off
	s_mov_b32 m0, s43
	s_nop 0
	global_load_lds_dwordx4 v[222:223], off
	s_waitcnt vmcnt(8)
	s_waitcnt lgkmcnt(0)
	s_barrier
	s_setprio 1
	s_waitcnt lgkmcnt(0)
	v_mfma_f32_16x16x32_bf16 v[60:63], v[144:147], v[176:179], v[60:63]
	v_mfma_f32_16x16x32_bf16 v[56:59], v[152:155], v[176:179], v[56:59]
	v_mfma_f32_16x16x32_bf16 v[44:47], v[144:147], v[184:187], v[44:47]
	v_mfma_f32_16x16x32_bf16 v[40:43], v[152:155], v[184:187], v[40:43]
	v_mfma_f32_16x16x32_bf16 v[28:31], v[144:147], v[200:203], v[28:31]
	v_mfma_f32_16x16x32_bf16 v[24:27], v[152:155], v[200:203], v[24:27]
	v_mfma_f32_16x16x32_bf16 v[12:15], v[144:147], v[208:211], v[12:15]
	v_mfma_f32_16x16x32_bf16 v[8:11], v[152:155], v[208:211], v[8:11]
	v_mfma_f32_16x16x32_bf16 v[60:63], v[148:151], v[180:183], v[60:63]
	v_mfma_f32_16x16x32_bf16 v[56:59], v[156:159], v[180:183], v[56:59]
	v_mfma_f32_16x16x32_bf16 v[44:47], v[148:151], v[196:199], v[44:47]
	v_mfma_f32_16x16x32_bf16 v[40:43], v[156:159], v[196:199], v[40:43]
	v_mfma_f32_16x16x32_bf16 v[28:31], v[148:151], v[204:207], v[28:31]
	v_mfma_f32_16x16x32_bf16 v[24:27], v[156:159], v[204:207], v[24:27]
	v_mfma_f32_16x16x32_bf16 v[12:15], v[148:151], v[212:215], v[12:15]
	v_mfma_f32_16x16x32_bf16 v[8:11], v[156:159], v[212:215], v[8:11]
	s_setprio 0
	s_setprio 1
	v_mfma_f32_16x16x32_bf16 v[52:55], v[160:163], v[176:179], v[52:55]
	v_mfma_f32_16x16x32_bf16 v[48:51], v[168:171], v[176:179], v[48:51]
	v_mfma_f32_16x16x32_bf16 v[36:39], v[160:163], v[184:187], v[36:39]
	v_mfma_f32_16x16x32_bf16 v[32:35], v[168:171], v[184:187], v[32:35]
	v_mfma_f32_16x16x32_bf16 v[20:23], v[160:163], v[200:203], v[20:23]
	v_mfma_f32_16x16x32_bf16 v[16:19], v[168:171], v[200:203], v[16:19]
	v_mfma_f32_16x16x32_bf16 v[4:7], v[160:163], v[208:211], v[4:7]
	v_mfma_f32_16x16x32_bf16 v[0:3], v[168:171], v[208:211], v[0:3]
	v_mfma_f32_16x16x32_bf16 v[52:55], v[164:167], v[180:183], v[52:55]
	v_mfma_f32_16x16x32_bf16 v[48:51], v[172:175], v[180:183], v[48:51]
	v_mfma_f32_16x16x32_bf16 v[36:39], v[164:167], v[196:199], v[36:39]
	v_mfma_f32_16x16x32_bf16 v[32:35], v[172:175], v[196:199], v[32:35]
	v_mfma_f32_16x16x32_bf16 v[20:23], v[164:167], v[204:207], v[20:23]
	v_mfma_f32_16x16x32_bf16 v[16:19], v[172:175], v[204:207], v[16:19]
	v_mfma_f32_16x16x32_bf16 v[4:7], v[164:167], v[212:215], v[4:7]
	v_mfma_f32_16x16x32_bf16 v[0:3], v[172:175], v[212:215], v[0:3]
	s_setprio 0
	s_barrier
	s_add_i32 s65, 0, 0x18000
	s_add_i32 s66, 0, 0x1c000
	v_add_u32_e32 v156, s65, v189
	v_add_u32_e32 v172, s66, v189
	ds_read_b128 v[144:147], v156
	ds_read_b128 v[148:151], v156 offset:1024
	ds_read_b128 v[152:155], v156 offset:2048
	ds_read_b128 v[156:159], v156 offset:3072
	ds_read_b128 v[160:163], v172
	ds_read_b128 v[164:167], v172 offset:1024
	ds_read_b128 v[168:171], v172 offset:2048
	ds_read_b128 v[172:175], v172 offset:3072
	s_add_u32 s38, s38, 0x80000
	s_addc_u32 s39, s39, 0
	s_mov_b32 m0, s44
	v_lshl_add_u64 v[224:225], s[38:39], 0, v[128:129]
	ds_read_b128 v[176:179], v193 offset:32768
	ds_read_b128 v[180:183], v193 offset:33792
	ds_read_b128 v[184:187], v193 offset:34816
	ds_read_b128 v[196:199], v193 offset:35840
	ds_read_b128 v[200:203], v193 offset:36864
	ds_read_b128 v[204:207], v193 offset:37888
	ds_read_b128 v[208:211], v193 offset:38912
	ds_read_b128 v[212:215], v193 offset:39936
	global_load_lds_dwordx4 v[224:225], off
	v_lshl_add_u64 v[224:225], s[38:39], 0, v[132:133]
	s_mov_b32 m0, s45
	s_nop 0
	global_load_lds_dwordx4 v[224:225], off
	s_waitcnt vmcnt(8)
	s_waitcnt lgkmcnt(0)
	s_barrier
	s_setprio 1
	s_waitcnt lgkmcnt(0)
	v_mfma_f32_16x16x32_bf16 v[124:127], v[144:147], v[176:179], v[124:127]
	v_mfma_f32_16x16x32_bf16 v[120:123], v[152:155], v[176:179], v[120:123]
	v_mfma_f32_16x16x32_bf16 v[108:111], v[144:147], v[184:187], v[108:111]
	v_mfma_f32_16x16x32_bf16 v[104:107], v[152:155], v[184:187], v[104:107]
	v_mfma_f32_16x16x32_bf16 v[92:95], v[144:147], v[200:203], v[92:95]
	v_mfma_f32_16x16x32_bf16 v[88:91], v[152:155], v[200:203], v[88:91]
	v_mfma_f32_16x16x32_bf16 v[76:79], v[144:147], v[208:211], v[76:79]
	v_mfma_f32_16x16x32_bf16 v[72:75], v[152:155], v[208:211], v[72:75]
	v_mfma_f32_16x16x32_bf16 v[124:127], v[148:151], v[180:183], v[124:127]
	v_mfma_f32_16x16x32_bf16 v[120:123], v[156:159], v[180:183], v[120:123]
	v_mfma_f32_16x16x32_bf16 v[108:111], v[148:151], v[196:199], v[108:111]
	v_mfma_f32_16x16x32_bf16 v[104:107], v[156:159], v[196:199], v[104:107]
	v_mfma_f32_16x16x32_bf16 v[92:95], v[148:151], v[204:207], v[92:95]
	v_mfma_f32_16x16x32_bf16 v[88:91], v[156:159], v[204:207], v[88:91]
	v_mfma_f32_16x16x32_bf16 v[76:79], v[148:151], v[212:215], v[76:79]
	v_mfma_f32_16x16x32_bf16 v[72:75], v[156:159], v[212:215], v[72:75]
	s_setprio 0
	s_setprio 1
	v_mfma_f32_16x16x32_bf16 v[116:119], v[160:163], v[176:179], v[116:119]
	v_mfma_f32_16x16x32_bf16 v[112:115], v[168:171], v[176:179], v[112:115]
	v_mfma_f32_16x16x32_bf16 v[100:103], v[160:163], v[184:187], v[100:103]
	v_mfma_f32_16x16x32_bf16 v[96:99], v[168:171], v[184:187], v[96:99]
	v_mfma_f32_16x16x32_bf16 v[84:87], v[160:163], v[200:203], v[84:87]
	v_mfma_f32_16x16x32_bf16 v[80:83], v[168:171], v[200:203], v[80:83]
	v_mfma_f32_16x16x32_bf16 v[68:71], v[160:163], v[208:211], v[68:71]
	v_mfma_f32_16x16x32_bf16 v[64:67], v[168:171], v[208:211], v[64:67]
	v_mfma_f32_16x16x32_bf16 v[116:119], v[164:167], v[180:183], v[116:119]
	v_mfma_f32_16x16x32_bf16 v[112:115], v[172:175], v[180:183], v[112:115]
	v_mfma_f32_16x16x32_bf16 v[100:103], v[164:167], v[196:199], v[100:103]
	v_mfma_f32_16x16x32_bf16 v[96:99], v[172:175], v[196:199], v[96:99]
	v_mfma_f32_16x16x32_bf16 v[84:87], v[164:167], v[204:207], v[84:87]
	v_mfma_f32_16x16x32_bf16 v[80:83], v[172:175], v[204:207], v[80:83]
	v_mfma_f32_16x16x32_bf16 v[68:71], v[164:167], v[212:215], v[68:71]
	v_mfma_f32_16x16x32_bf16 v[64:67], v[172:175], v[212:215], v[64:67]
	s_setprio 0
	s_barrier
	s_add_i32 s38, s65, s3
	v_lshl_add_u64 v[216:217], v[216:217], 0, s[18:19]
	s_mov_b32 m0, s38
	ds_read_b128 v[176:179], v193 offset:49152
	ds_read_b128 v[180:183], v193 offset:50176
	ds_read_b128 v[184:187], v193 offset:51200
	ds_read_b128 v[196:199], v193 offset:52224
	ds_read_b128 v[200:203], v193 offset:53248
	ds_read_b128 v[204:207], v193 offset:54272
	ds_read_b128 v[208:211], v193 offset:55296
	ds_read_b128 v[212:215], v193 offset:56320
	global_load_lds_dwordx4 v[216:217], off
	s_add_i32 m0, s38, 0x2000
	s_add_u32 s36, s36, 0x80080
	v_lshl_add_u64 v[216:217], v[218:219], 0, s[18:19]
	s_addc_u32 s37, s37, 0
	s_add_i32 s38, s66, s3
	global_load_lds_dwordx4 v[216:217], off
	v_lshl_add_u64 v[216:217], s[36:37], 0, v[130:131]
	s_mov_b32 m0, s38
	s_nop 0
	global_load_lds_dwordx4 v[216:217], off
	v_lshl_add_u64 v[216:217], s[36:37], 0, v[134:135]
	s_add_i32 m0, s38, 0x2000
	s_nop 0
	global_load_lds_dwordx4 v[216:217], off
	v_lshl_add_u64 v[216:217], v[220:221], 0, s[18:19]
	s_mov_b32 m0, s54
	s_nop 0
	global_load_lds_dwordx4 v[216:217], off
	v_lshl_add_u64 v[216:217], v[222:223], 0, s[18:19]
	s_mov_b32 m0, s55
	s_nop 0
	global_load_lds_dwordx4 v[216:217], off
	s_waitcnt vmcnt(8)
	s_waitcnt lgkmcnt(0)
	s_barrier
	s_setprio 1
	s_waitcnt lgkmcnt(0)
	v_mfma_f32_16x16x32_bf16 v[60:63], v[144:147], v[176:179], v[60:63]
	v_mfma_f32_16x16x32_bf16 v[56:59], v[152:155], v[176:179], v[56:59]
	v_mfma_f32_16x16x32_bf16 v[44:47], v[144:147], v[184:187], v[44:47]
	v_mfma_f32_16x16x32_bf16 v[40:43], v[152:155], v[184:187], v[40:43]
	v_mfma_f32_16x16x32_bf16 v[28:31], v[144:147], v[200:203], v[28:31]
	v_mfma_f32_16x16x32_bf16 v[24:27], v[152:155], v[200:203], v[24:27]
	v_mfma_f32_16x16x32_bf16 v[12:15], v[144:147], v[208:211], v[12:15]
	v_mfma_f32_16x16x32_bf16 v[8:11], v[152:155], v[208:211], v[8:11]
	v_mfma_f32_16x16x32_bf16 v[60:63], v[148:151], v[180:183], v[60:63]
	v_mfma_f32_16x16x32_bf16 v[56:59], v[156:159], v[180:183], v[56:59]
	v_mfma_f32_16x16x32_bf16 v[44:47], v[148:151], v[196:199], v[44:47]
	v_mfma_f32_16x16x32_bf16 v[40:43], v[156:159], v[196:199], v[40:43]
	v_mfma_f32_16x16x32_bf16 v[28:31], v[148:151], v[204:207], v[28:31]
	v_mfma_f32_16x16x32_bf16 v[24:27], v[156:159], v[204:207], v[24:27]
	v_mfma_f32_16x16x32_bf16 v[12:15], v[148:151], v[212:215], v[12:15]
	v_mfma_f32_16x16x32_bf16 v[8:11], v[156:159], v[212:215], v[8:11]
	s_setprio 0
	s_setprio 1
	v_mfma_f32_16x16x32_bf16 v[52:55], v[160:163], v[176:179], v[52:55]
	s_add_i32 s64, s64, 2
	v_mfma_f32_16x16x32_bf16 v[48:51], v[168:171], v[176:179], v[48:51]
	s_add_u32 s34, s34, 0x100
	v_mfma_f32_16x16x32_bf16 v[36:39], v[160:163], v[184:187], v[36:39]
	s_addc_u32 s35, s35, 0
	v_mfma_f32_16x16x32_bf16 v[32:35], v[168:171], v[184:187], v[32:35]
	s_add_u32 s62, s62, 0x100
	v_mfma_f32_16x16x32_bf16 v[20:23], v[160:163], v[200:203], v[20:23]
	s_addc_u32 s63, s63, 0
	v_mfma_f32_16x16x32_bf16 v[16:19], v[168:171], v[200:203], v[16:19]
	s_cmp_gt_u32 s64, 29
	v_mfma_f32_16x16x32_bf16 v[4:7], v[160:163], v[208:211], v[4:7]
	v_mfma_f32_16x16x32_bf16 v[0:3], v[168:171], v[208:211], v[0:3]
	v_mfma_f32_16x16x32_bf16 v[52:55], v[164:167], v[180:183], v[52:55]
	v_mfma_f32_16x16x32_bf16 v[48:51], v[172:175], v[180:183], v[48:51]
	v_mfma_f32_16x16x32_bf16 v[36:39], v[164:167], v[196:199], v[36:39]
	v_mfma_f32_16x16x32_bf16 v[32:35], v[172:175], v[196:199], v[32:35]
	v_mfma_f32_16x16x32_bf16 v[20:23], v[164:167], v[204:207], v[20:23]
	v_mfma_f32_16x16x32_bf16 v[16:19], v[172:175], v[204:207], v[16:19]
	v_mfma_f32_16x16x32_bf16 v[4:7], v[164:167], v[212:215], v[4:7]
	v_mfma_f32_16x16x32_bf16 v[0:3], v[172:175], v[212:215], v[0:3]
	s_setprio 0
	s_barrier
	s_cbranch_scc0 .LBB0_1356
	s_and_b64 vcc, exec, s[20:21]
	s_cbranch_vccz .LBB0_1359
	s_barrier
